# merged the adjacent s_waitcnt vmcnt(8) and s_waitcnt lgkmcnt(0) before 24 load-segment barriers into one instruction
# baseline (speedup 1.0000x reference)
; #define PG8_STAGE(bufoff, gbase, voff) do { _Pragma("unroll") for (int _i = 0; _i < 2; ++_i) \
;         __builtin_amdgcn_global_load_lds((const unsigned*)((const char*)(gbase) + (voff)[_i]), (PG8_LAS unsigned*)(lds + (bufoff) + ldsw + _i * 8192), 16, 0, 0); } while (0)
; #define PG8_LDA(dst, b, h) do { _Pragma("unroll") for (int m = 0; m < 4; ++m) _Pragma("unroll") for (int k = 0; k < 2; ++k) dst[m][k] = *(const PG8_LAS bf16x8*)(lds + PG8_SA(b, h) + aoff + m * 2048 + k * 1024); } while (0)
; #define PG8_MMA(ai, bj, At, Bt) do { __builtin_amdgcn_s_setprio(1); _Pragma("unroll") for (int m = 0; m < 4; ++m) _Pragma("unroll") for (int n = 0; n < 2; ++n) _Pragma("unroll") for (int k = 0; k < 2; ++k) \
;         acc[ai][bj][m][n] = __builtin_amdgcn_mfma_f32_16x16x32_bf16(Bt[n][k], At[m][k], acc[ai][bj][m][n], 0, 0, 0); __builtin_amdgcn_s_setprio(0); } while (0)
; #define PG8_WAIT_V(n) asm volatile("s_waitcnt vmcnt(" #n ")" ::: "memory")
; #define PG8_WAIT_L(n) asm volatile("s_waitcnt lgkmcnt(" #n ")" ::: "memory")
; #define PG8_BAR __builtin_amdgcn_s_barrier()
; #define PG8_SCHED __builtin_amdgcn_sched_barrier(0)
; template <class Epi, class Sched, bool ALIGN_EPI = false, bool SP2 = false>
; __device__ __forceinline__ void gemm_phase(PG8_LAS unsigned char* lds, const Gemm g, const Sched& S, const Epi& E) {
;     ...
;             PG8_WAIT_V(8); PG8_WAIT_L(0); PG8_BAR; PG8_MMA(0, 0, At, B0); PG8_MMA(0, 1, At, B1); PG8_BAR; PG8_SCHED;
;             PG8_LDA(At, 1, 1); PG8_STAGE(PG8_SB(1, 0), b3, voffB); PG8_STAGE(PG8_SB(1, 1), b3 + hstep, voffB); PG8_STAGE(PG8_SA(1, 0), a3, voffA);
;             PG8_WAIT_V(8); PG8_WAIT_L(0); PG8_BAR; PG8_MMA(1, 0, At, B0); PG8_MMA(1, 1, At, B1); PG8_BAR; PG8_SCHED;
;     ...
;         if constexpr (ALIGN_EPI) { if (wr == 0) PG8_BAR; }
.Lgr_p1_2:
	s_waitcnt lgkmcnt(0)
	s_barrier
	s_setprio 1
	v_mfma_f32_16x16x32_bf16 v[116:119], v[152:155], v[184:187], v[116:119]
	v_mfma_f32_16x16x32_bf16 v[112:115], v[160:163], v[184:187], v[112:115]
	v_mfma_f32_16x16x32_bf16 v[108:111], v[152:155], v[192:195], v[108:111]
	v_mfma_f32_16x16x32_bf16 v[100:103], v[160:163], v[192:195], v[100:103]
	v_mfma_f32_16x16x32_bf16 v[92:95], v[152:155], v[200:203], v[92:95]
	v_mfma_f32_16x16x32_bf16 v[84:87], v[160:163], v[200:203], v[84:87]
	v_mfma_f32_16x16x32_bf16 v[76:79], v[152:155], v[210:213], v[76:79]
	v_mfma_f32_16x16x32_bf16 v[68:71], v[160:163], v[210:213], v[68:71]
	v_mfma_f32_16x16x32_bf16 v[116:119], v[156:159], v[188:191], v[116:119]
	v_mfma_f32_16x16x32_bf16 v[112:115], v[164:167], v[188:191], v[112:115]
	v_mfma_f32_16x16x32_bf16 v[108:111], v[156:159], v[196:199], v[108:111]
	v_mfma_f32_16x16x32_bf16 v[100:103], v[164:167], v[196:199], v[100:103]
	v_mfma_f32_16x16x32_bf16 v[92:95], v[156:159], v[206:209], v[92:95]
	v_mfma_f32_16x16x32_bf16 v[84:87], v[164:167], v[206:209], v[84:87]
	v_mfma_f32_16x16x32_bf16 v[76:79], v[156:159], v[214:217], v[76:79]
	v_mfma_f32_16x16x32_bf16 v[68:71], v[164:167], v[214:217], v[68:71]
	s_setprio 0
	s_setprio 1
	v_mfma_f32_16x16x32_bf16 v[124:127], v[168:171], v[184:187], v[124:127]
	v_mfma_f32_16x16x32_bf16 v[120:123], v[176:179], v[184:187], v[120:123]
	v_mfma_f32_16x16x32_bf16 v[104:107], v[168:171], v[192:195], v[104:107]
	v_mfma_f32_16x16x32_bf16 v[96:99], v[176:179], v[192:195], v[96:99]
	v_mfma_f32_16x16x32_bf16 v[88:91], v[168:171], v[200:203], v[88:91]
	v_mfma_f32_16x16x32_bf16 v[80:83], v[176:179], v[200:203], v[80:83]
	v_mfma_f32_16x16x32_bf16 v[72:75], v[168:171], v[210:213], v[72:75]
	v_mfma_f32_16x16x32_bf16 v[64:67], v[176:179], v[210:213], v[64:67]
	v_mfma_f32_16x16x32_bf16 v[124:127], v[172:175], v[188:191], v[124:127]
	v_mfma_f32_16x16x32_bf16 v[120:123], v[180:183], v[188:191], v[120:123]
	v_mfma_f32_16x16x32_bf16 v[104:107], v[172:175], v[196:199], v[104:107]
	v_mfma_f32_16x16x32_bf16 v[96:99], v[180:183], v[196:199], v[96:99]
	v_mfma_f32_16x16x32_bf16 v[88:91], v[172:175], v[206:209], v[88:91]
	v_mfma_f32_16x16x32_bf16 v[80:83], v[180:183], v[206:209], v[80:83]
	v_mfma_f32_16x16x32_bf16 v[72:75], v[172:175], v[214:217], v[72:75]
	v_mfma_f32_16x16x32_bf16 v[64:67], v[180:183], v[214:217], v[64:67]
	s_setprio 0
	s_barrier
	s_add_i32 s26, s52, s0
	s_mov_b32 m0, s26
	ds_read_b128 v[184:187], v149 offset:49152
	ds_read_b128 v[188:191], v149 offset:50176
	ds_read_b128 v[192:195], v149 offset:51200
	ds_read_b128 v[196:199], v149 offset:52224
	global_load_lds_dwordx4 v132, vcc
	s_add_i32 m0, s26, 0x2000
	s_add_u32 s24, s24, 0x80080
	s_addc_u32 s25, s25, 0
	s_add_i32 s26, s53, s0
	global_load_lds_dwordx4 v128, vcc
	s_mov_b32 m0, s26
	ds_read_b128 v[214:217], v149 offset:56320
	global_load_lds_dwordx4 v132, s[24:25]
	s_add_i32 m0, s26, 0x2000
	ds_read_b128 v[210:213], v149 offset:55296
	global_load_lds_dwordx4 v128, s[24:25]
	s_mov_b32 m0, s35
	ds_read_b128 v[206:209], v149 offset:54272
	global_load_lds_dwordx4 v134, s[98:99]
	s_mov_b32 m0, s40
	ds_read_b128 v[200:203], v149 offset:53248
	global_load_lds_dwordx4 v130, s[98:99]
	s_waitcnt vmcnt(8) lgkmcnt(0)
	s_barrier
	s_setprio 1
	v_mfma_f32_16x16x32_bf16 v[60:63], v[152:155], v[184:187], v[60:63]
	v_mfma_f32_16x16x32_bf16 v[52:55], v[160:163], v[184:187], v[52:55]
	v_mfma_f32_16x16x32_bf16 v[44:47], v[152:155], v[192:195], v[44:47]
	v_mfma_f32_16x16x32_bf16 v[36:39], v[160:163], v[192:195], v[36:39]
	v_mfma_f32_16x16x32_bf16 v[28:31], v[152:155], v[200:203], v[28:31]
	v_mfma_f32_16x16x32_bf16 v[20:23], v[160:163], v[200:203], v[20:23]
	v_mfma_f32_16x16x32_bf16 v[12:15], v[152:155], v[210:213], v[12:15]
	v_mfma_f32_16x16x32_bf16 v[4:7], v[160:163], v[210:213], v[4:7]
	v_mfma_f32_16x16x32_bf16 v[60:63], v[156:159], v[188:191], v[60:63]
	v_mfma_f32_16x16x32_bf16 v[52:55], v[164:167], v[188:191], v[52:55]
	v_mfma_f32_16x16x32_bf16 v[44:47], v[156:159], v[196:199], v[44:47]
	v_mfma_f32_16x16x32_bf16 v[36:39], v[164:167], v[196:199], v[36:39]
	v_mfma_f32_16x16x32_bf16 v[28:31], v[156:159], v[206:209], v[28:31]
	v_mfma_f32_16x16x32_bf16 v[20:23], v[164:167], v[206:209], v[20:23]
	v_mfma_f32_16x16x32_bf16 v[12:15], v[156:159], v[214:217], v[12:15]
	v_mfma_f32_16x16x32_bf16 v[4:7], v[164:167], v[214:217], v[4:7]
	s_setprio 0
	s_setprio 1
	v_mfma_f32_16x16x32_bf16 v[56:59], v[168:171], v[184:187], v[56:59]
	v_mfma_f32_16x16x32_bf16 v[48:51], v[176:179], v[184:187], v[48:51]
	v_mfma_f32_16x16x32_bf16 v[40:43], v[168:171], v[192:195], v[40:43]
	v_mfma_f32_16x16x32_bf16 v[32:35], v[176:179], v[192:195], v[32:35]
	v_mfma_f32_16x16x32_bf16 v[24:27], v[168:171], v[200:203], v[24:27]
	v_mfma_f32_16x16x32_bf16 v[16:19], v[176:179], v[200:203], v[16:19]
	v_mfma_f32_16x16x32_bf16 v[8:11], v[168:171], v[210:213], v[8:11]
	v_mfma_f32_16x16x32_bf16 v[0:3], v[176:179], v[210:213], v[0:3]
	v_mfma_f32_16x16x32_bf16 v[56:59], v[172:175], v[188:191], v[56:59]
	v_mfma_f32_16x16x32_bf16 v[48:51], v[180:183], v[188:191], v[48:51]
	v_mfma_f32_16x16x32_bf16 v[40:43], v[172:175], v[196:199], v[40:43]
	v_mfma_f32_16x16x32_bf16 v[32:35], v[180:183], v[196:199], v[32:35]
	v_mfma_f32_16x16x32_bf16 v[24:27], v[172:175], v[206:209], v[24:27]
	v_mfma_f32_16x16x32_bf16 v[16:19], v[180:183], v[206:209], v[16:19]
	v_mfma_f32_16x16x32_bf16 v[8:11], v[172:175], v[214:217], v[8:11]
	v_mfma_f32_16x16x32_bf16 v[0:3], v[180:183], v[214:217], v[0:3]
	s_setprio 0
	s_barrier
	s_mov_b32 s100, 0
	s_add_i32 s51, s51, 2
	s_add_u32 s22, s22, 0x100
	s_addc_u32 s23, s23, 0
	s_add_u32 s49, s49, 0x100
	s_addc_u32 s50, s50, 0
	s_cmp_gt_u32 s51, 29
	s_cbranch_scc0 .LBB0_204
	s_and_b64 vcc, exec, s[12:13]
	s_cbranch_vccz .LBB0_207
	s_barrier

; #define PG8_STAGE(bufoff, gbase, voff) do { _Pragma("unroll") for (int _i = 0; _i < 2; ++_i) \
;         __builtin_amdgcn_global_load_lds((const unsigned*)((const char*)(gbase) + (voff)[_i]), (PG8_LAS unsigned*)(lds + (bufoff) + ldsw + _i * 8192), 16, 0, 0); } while (0)
; #define PG8_LDA(dst, b, h) do { _Pragma("unroll") for (int m = 0; m < 4; ++m) _Pragma("unroll") for (int k = 0; k < 2; ++k) dst[m][k] = *(const PG8_LAS bf16x8*)(lds + PG8_SA(b, h) + aoff + m * 2048 + k * 1024); } while (0)
; #define PG8_LDB(dst, b, h) do { _Pragma("unroll") for (int n = 0; n < 2; ++n) _Pragma("unroll") for (int k = 0; k < 2; ++k) dst[n][k] = *(const PG8_LAS bf16x8*)(lds + PG8_SB(b, h) + boff + n * 2048 + k * 1024); } while (0)
; #define PG8_MMA(ai, bj, At, Bt) do { __builtin_amdgcn_s_setprio(1); _Pragma("unroll") for (int m = 0; m < 4; ++m) _Pragma("unroll") for (int n = 0; n < 2; ++n) _Pragma("unroll") for (int k = 0; k < 2; ++k) \
;         acc[ai][bj][m][n] = __builtin_amdgcn_mfma_f32_16x16x32_bf16(Bt[n][k], At[m][k], acc[ai][bj][m][n], 0, 0, 0); __builtin_amdgcn_s_setprio(0); } while (0)
; #define PG8_WAIT_V(n) asm volatile("s_waitcnt vmcnt(" #n ")" ::: "memory")
; #define PG8_WAIT_L(n) asm volatile("s_waitcnt lgkmcnt(" #n ")" ::: "memory")
; template <class Epi, class Sched, bool ALIGN_EPI = false, bool SP2 = false>
; __device__ __forceinline__ void gemm_phase(PG8_LAS unsigned char* lds, const Gemm g, const Sched& S, const Epi& E) {
;     ...
;             const bool last = (t == nt - 2);
;             const char* a1 = cA + (size_t)(t + 1) * kstep;
;             const char* a2 = last ? nA : cA + (size_t)(t + 2) * kstep; const char* b2 = last ? nB : cB + (size_t)(t + 2) * kstep;
;             const char* a3 = a2 + kstep; const char* b3 = b2 + kstep;
;             if (last && has_next) S.a_ready(nxt);
;             if constexpr (SP2) {
;             PG8_LDB(B0, 0, 0); PG8_LDB(B1, 0, 1); PG8_SCHED; PG8_LDA(At, 0, 0); PG8_STAGE(PG8_SA(1, 1), a1 + hstep, voffA);
;             PG8_WAIT_V(8); PG8_WAIT_L(0); PG8_BAR; PG8_MMA(0, 0, At, B0); PG8_MMA(0, 1, At, B1); PG8_BAR; PG8_SCHED;
;             PG8_LDA(At, 0, 1); PG8_STAGE(PG8_SB(0, 0), b2, voffB); PG8_STAGE(PG8_SB(0, 1), b2 + hstep, voffB); PG8_STAGE(PG8_SA(0, 0), a2, voffA);
;             PG8_WAIT_V(8); PG8_WAIT_L(0); PG8_BAR; PG8_MMA(1, 0, At, B0); PG8_MMA(1, 1, At, B1); PG8_BAR; PG8_SCHED;
.LBB0_285:
	ds_read_b128 v[128:131], v208
	ds_read_b128 v[132:135], v208 offset:1024
	ds_read_b128 v[136:139], v208 offset:2048
	ds_read_b128 v[140:143], v208 offset:3072
	ds_read_b128 v[144:147], v209
	ds_read_b128 v[148:151], v209 offset:1024
	ds_read_b128 v[152:155], v209 offset:2048
	ds_read_b128 v[156:159], v209 offset:3072
	s_add_u32 s22, s20, 0xffea0080
	s_addc_u32 s23, s21, -1
	s_cmpk_eq_i32 s48, 0x54
	s_cselect_b32 s25, s7, s23
	s_cselect_b32 s24, s6, s22
	s_cselect_b32 s23, s19, s47
	s_cselect_b32 s22, s18, s46
	s_add_i32 m0, s1, 0xc000
	ds_read_b128 v[160:163], v210
	ds_read_b128 v[164:167], v210 offset:1024
	ds_read_b128 v[168:171], v210 offset:2048
	ds_read_b128 v[172:175], v210 offset:3072
	ds_read_b128 v[192:195], v210 offset:4096
	ds_read_b128 v[196:199], v210 offset:5120
	ds_read_b128 v[200:203], v210 offset:6144
	global_load_lds_dwordx4 v184, s[20:21]
	s_add_i32 m0, s1, 0xe000
	ds_read_b128 v[212:215], v210 offset:7168
	global_load_lds_dwordx4 v186, s[20:21]
	s_waitcnt vmcnt(8) lgkmcnt(0)
	s_barrier
	s_setprio 1
	v_mfma_f32_16x16x32_bf16 v[124:127], v[128:131], v[160:163], v[124:127]
	v_mfma_f32_16x16x32_bf16 v[120:123], v[136:139], v[160:163], v[120:123]
	v_mfma_f32_16x16x32_bf16 v[108:111], v[128:131], v[168:171], v[108:111]
	v_mfma_f32_16x16x32_bf16 v[104:107], v[136:139], v[168:171], v[104:107]
	v_mfma_f32_16x16x32_bf16 v[92:95], v[128:131], v[192:195], v[92:95]
	v_mfma_f32_16x16x32_bf16 v[88:91], v[136:139], v[192:195], v[88:91]
	v_mfma_f32_16x16x32_bf16 v[76:79], v[128:131], v[200:203], v[76:79]
	v_mfma_f32_16x16x32_bf16 v[72:75], v[136:139], v[200:203], v[72:75]
	v_mfma_f32_16x16x32_bf16 v[124:127], v[132:135], v[164:167], v[124:127]
	v_mfma_f32_16x16x32_bf16 v[120:123], v[140:143], v[164:167], v[120:123]
	v_mfma_f32_16x16x32_bf16 v[108:111], v[132:135], v[172:175], v[108:111]
	v_mfma_f32_16x16x32_bf16 v[104:107], v[140:143], v[172:175], v[104:107]
	v_mfma_f32_16x16x32_bf16 v[92:95], v[132:135], v[196:199], v[92:95]
	v_mfma_f32_16x16x32_bf16 v[88:91], v[140:143], v[196:199], v[88:91]
	v_mfma_f32_16x16x32_bf16 v[76:79], v[132:135], v[212:215], v[76:79]
	v_mfma_f32_16x16x32_bf16 v[72:75], v[140:143], v[212:215], v[72:75]
	s_setprio 0
	s_setprio 1
	v_mfma_f32_16x16x32_bf16 v[116:119], v[144:147], v[160:163], v[116:119]
	v_mfma_f32_16x16x32_bf16 v[112:115], v[152:155], v[160:163], v[112:115]
	v_mfma_f32_16x16x32_bf16 v[100:103], v[144:147], v[168:171], v[100:103]
	v_mfma_f32_16x16x32_bf16 v[96:99], v[152:155], v[168:171], v[96:99]
	v_mfma_f32_16x16x32_bf16 v[84:87], v[144:147], v[192:195], v[84:87]
	v_mfma_f32_16x16x32_bf16 v[80:83], v[152:155], v[192:195], v[80:83]
	v_mfma_f32_16x16x32_bf16 v[68:71], v[144:147], v[200:203], v[68:71]
	v_mfma_f32_16x16x32_bf16 v[64:67], v[152:155], v[200:203], v[64:67]
	v_mfma_f32_16x16x32_bf16 v[116:119], v[148:151], v[164:167], v[116:119]
	v_mfma_f32_16x16x32_bf16 v[112:115], v[156:159], v[164:167], v[112:115]
	v_mfma_f32_16x16x32_bf16 v[100:103], v[148:151], v[172:175], v[100:103]
	v_mfma_f32_16x16x32_bf16 v[96:99], v[156:159], v[172:175], v[96:99]
	v_mfma_f32_16x16x32_bf16 v[84:87], v[148:151], v[196:199], v[84:87]
	v_mfma_f32_16x16x32_bf16 v[80:83], v[156:159], v[196:199], v[80:83]
	v_mfma_f32_16x16x32_bf16 v[68:71], v[148:151], v[212:215], v[68:71]
	v_mfma_f32_16x16x32_bf16 v[64:67], v[156:159], v[212:215], v[64:67]
	s_setprio 0
	s_barrier
	s_add_i32 s49, s40, s0
	s_add_u32 vcc_lo, s22, 0x80
	s_addc_u32 vcc_hi, s23, 0
	s_mov_b32 m0, s49
	ds_read_b128 v[160:163], v210 offset:16384
	ds_read_b128 v[164:167], v210 offset:17408
	ds_read_b128 v[168:171], v210 offset:18432
	ds_read_b128 v[172:175], v210 offset:19456
	global_load_lds_dwordx4 v178, s[22:23]
	s_add_i32 m0, s49, 0x2000
	s_add_u32 s50, s22, 0x160000
	s_addc_u32 s51, s23, 0
	s_add_i32 s49, s41, s0
	global_load_lds_dwordx4 v182, s[22:23]
	s_mov_b32 m0, s49
	ds_read_b128 v[212:215], v210 offset:23552
	global_load_lds_dwordx4 v178, s[50:51]
	s_add_i32 m0, s49, 0x2000
	ds_read_b128 v[200:203], v210 offset:22528
	global_load_lds_dwordx4 v182, s[50:51]
	s_add_u32 s98, s24, 0x80
	s_addc_u32 s99, s25, 0
	s_mov_b32 m0, s1
	ds_read_b128 v[196:199], v210 offset:21504
	global_load_lds_dwordx4 v176, s[24:25]
	s_mov_b32 m0, s26
	ds_read_b128 v[192:195], v210 offset:20480
	global_load_lds_dwordx4 v180, s[24:25]
	s_waitcnt vmcnt(8) lgkmcnt(0)
	s_barrier
	s_setprio 1
	v_mfma_f32_16x16x32_bf16 v[60:63], v[128:131], v[160:163], v[60:63]
	v_mfma_f32_16x16x32_bf16 v[56:59], v[136:139], v[160:163], v[56:59]
	v_mfma_f32_16x16x32_bf16 v[44:47], v[128:131], v[168:171], v[44:47]
	v_mfma_f32_16x16x32_bf16 v[40:43], v[136:139], v[168:171], v[40:43]
	v_mfma_f32_16x16x32_bf16 v[28:31], v[128:131], v[192:195], v[28:31]
	v_mfma_f32_16x16x32_bf16 v[24:27], v[136:139], v[192:195], v[24:27]
	v_mfma_f32_16x16x32_bf16 v[12:15], v[128:131], v[200:203], v[12:15]
	v_mfma_f32_16x16x32_bf16 v[8:11], v[136:139], v[200:203], v[8:11]
	v_mfma_f32_16x16x32_bf16 v[60:63], v[132:135], v[164:167], v[60:63]
	v_mfma_f32_16x16x32_bf16 v[56:59], v[140:143], v[164:167], v[56:59]
	v_mfma_f32_16x16x32_bf16 v[44:47], v[132:135], v[172:175], v[44:47]
	v_mfma_f32_16x16x32_bf16 v[40:43], v[140:143], v[172:175], v[40:43]
	v_mfma_f32_16x16x32_bf16 v[28:31], v[132:135], v[196:199], v[28:31]
	v_mfma_f32_16x16x32_bf16 v[24:27], v[140:143], v[196:199], v[24:27]
	v_mfma_f32_16x16x32_bf16 v[12:15], v[132:135], v[212:215], v[12:15]
	v_mfma_f32_16x16x32_bf16 v[8:11], v[140:143], v[212:215], v[8:11]
	s_setprio 0
	s_setprio 1
	v_mfma_f32_16x16x32_bf16 v[52:55], v[144:147], v[160:163], v[52:55]
	v_mfma_f32_16x16x32_bf16 v[48:51], v[152:155], v[160:163], v[48:51]
	v_mfma_f32_16x16x32_bf16 v[36:39], v[144:147], v[168:171], v[36:39]
	v_mfma_f32_16x16x32_bf16 v[32:35], v[152:155], v[168:171], v[32:35]
	v_mfma_f32_16x16x32_bf16 v[20:23], v[144:147], v[192:195], v[20:23]
	v_mfma_f32_16x16x32_bf16 v[16:19], v[152:155], v[192:195], v[16:19]
	v_mfma_f32_16x16x32_bf16 v[4:7], v[144:147], v[200:203], v[4:7]
	v_mfma_f32_16x16x32_bf16 v[0:3], v[152:155], v[200:203], v[0:3]
	v_mfma_f32_16x16x32_bf16 v[52:55], v[148:151], v[164:167], v[52:55]
	v_mfma_f32_16x16x32_bf16 v[48:51], v[156:159], v[164:167], v[48:51]
	v_mfma_f32_16x16x32_bf16 v[36:39], v[148:151], v[172:175], v[36:39]
	v_mfma_f32_16x16x32_bf16 v[32:35], v[156:159], v[172:175], v[32:35]
	v_mfma_f32_16x16x32_bf16 v[20:23], v[148:151], v[196:199], v[20:23]
	v_mfma_f32_16x16x32_bf16 v[16:19], v[156:159], v[196:199], v[16:19]
	v_mfma_f32_16x16x32_bf16 v[4:7], v[148:151], v[212:215], v[4:7]
	v_mfma_f32_16x16x32_bf16 v[0:3], v[156:159], v[212:215], v[0:3]
	s_setprio 0
	s_barrier
; #define PG8_STAGE(bufoff, gbase, voff) do { _Pragma("unroll") for (int _i = 0; _i < 2; ++_i) \
;         __builtin_amdgcn_global_load_lds((const unsigned*)((const char*)(gbase) + (voff)[_i]), (PG8_LAS unsigned*)(lds + (bufoff) + ldsw + _i * 8192), 16, 0, 0); } while (0)
; #define PG8_LDA(dst, b, h) do { _Pragma("unroll") for (int m = 0; m < 4; ++m) _Pragma("unroll") for (int k = 0; k < 2; ++k) dst[m][k] = *(const PG8_LAS bf16x8*)(lds + PG8_SA(b, h) + aoff + m * 2048 + k * 1024); } while (0)
; #define PG8_LDB(dst, b, h) do { _Pragma("unroll") for (int n = 0; n < 2; ++n) _Pragma("unroll") for (int k = 0; k < 2; ++k) dst[n][k] = *(const PG8_LAS bf16x8*)(lds + PG8_SB(b, h) + boff + n * 2048 + k * 1024); } while (0)
; #define PG8_MMA(ai, bj, At, Bt) do { __builtin_amdgcn_s_setprio(1); _Pragma("unroll") for (int m = 0; m < 4; ++m) _Pragma("unroll") for (int n = 0; n < 2; ++n) _Pragma("unroll") for (int k = 0; k < 2; ++k) \
;         acc[ai][bj][m][n] = __builtin_amdgcn_mfma_f32_16x16x32_bf16(Bt[n][k], At[m][k], acc[ai][bj][m][n], 0, 0, 0); __builtin_amdgcn_s_setprio(0); } while (0)
; #define PG8_WAIT_V(n) asm volatile("s_waitcnt vmcnt(" #n ")" ::: "memory")
; #define PG8_WAIT_L(n) asm volatile("s_waitcnt lgkmcnt(" #n ")" ::: "memory")
; #define PG8_BAR __builtin_amdgcn_s_barrier()
; #define PG8_SCHED __builtin_amdgcn_sched_barrier(0)
; template <class Epi, class Sched, bool ALIGN_EPI = false, bool SP2 = false>
; __device__ __forceinline__ void gemm_phase(PG8_LAS unsigned char* lds, const Gemm g, const Sched& S, const Epi& E) {
;     ...
;             PG8_LDB(B0, 1, 0); PG8_LDB(B1, 1, 1); PG8_SCHED; PG8_LDA(At, 1, 0); PG8_STAGE(PG8_SA(0, 1), a2 + hstep, voffA);
;             PG8_WAIT_V(8); PG8_WAIT_L(0); PG8_BAR; PG8_MMA(0, 0, At, B0); PG8_MMA(0, 1, At, B1); PG8_BAR; PG8_SCHED;
;             PG8_LDA(At, 1, 1); PG8_STAGE(PG8_SB(1, 0), b3, voffB); PG8_STAGE(PG8_SB(1, 1), b3 + hstep, voffB); PG8_STAGE(PG8_SA(1, 0), a3, voffA);
;             PG8_WAIT_V(8); PG8_WAIT_L(0); PG8_BAR; PG8_MMA(1, 0, At, B0); PG8_MMA(1, 1, At, B1); PG8_BAR; PG8_SCHED;
;     ...
;         if constexpr (ALIGN_EPI) { if (wr == 0) PG8_BAR; }
	s_add_i32 s49, 0, 0x18000
	s_add_i32 s50, 0, 0x1c000
	v_add_u32_e32 v140, s49, v206
	v_add_u32_e32 v156, s50, v206
	ds_read_b128 v[128:131], v140
	ds_read_b128 v[132:135], v140 offset:1024
	ds_read_b128 v[136:139], v140 offset:2048
	ds_read_b128 v[140:143], v140 offset:3072
	ds_read_b128 v[144:147], v156
	ds_read_b128 v[148:151], v156 offset:1024
	ds_read_b128 v[152:155], v156 offset:2048
	ds_read_b128 v[156:159], v156 offset:3072
	s_add_u32 s24, s24, 0x160000
	s_addc_u32 s25, s25, 0
	s_mov_b32 m0, s27
	ds_read_b128 v[160:163], v210 offset:32768
	ds_read_b128 v[164:167], v210 offset:33792
	ds_read_b128 v[168:171], v210 offset:34816
	ds_read_b128 v[172:175], v210 offset:35840
	ds_read_b128 v[192:195], v210 offset:36864
	ds_read_b128 v[196:199], v210 offset:37888
	ds_read_b128 v[200:203], v210 offset:38912
	global_load_lds_dwordx4 v176, s[24:25]
	s_mov_b32 m0, s28
	ds_read_b128 v[212:215], v210 offset:39936
	global_load_lds_dwordx4 v180, s[24:25]
	s_waitcnt vmcnt(8) lgkmcnt(0)
	s_barrier
	s_setprio 1
	v_mfma_f32_16x16x32_bf16 v[124:127], v[128:131], v[160:163], v[124:127]
	v_mfma_f32_16x16x32_bf16 v[120:123], v[136:139], v[160:163], v[120:123]
	v_mfma_f32_16x16x32_bf16 v[108:111], v[128:131], v[168:171], v[108:111]
	v_mfma_f32_16x16x32_bf16 v[104:107], v[136:139], v[168:171], v[104:107]
	v_mfma_f32_16x16x32_bf16 v[92:95], v[128:131], v[192:195], v[92:95]
	v_mfma_f32_16x16x32_bf16 v[88:91], v[136:139], v[192:195], v[88:91]
	v_mfma_f32_16x16x32_bf16 v[76:79], v[128:131], v[200:203], v[76:79]
	v_mfma_f32_16x16x32_bf16 v[72:75], v[136:139], v[200:203], v[72:75]
	v_mfma_f32_16x16x32_bf16 v[124:127], v[132:135], v[164:167], v[124:127]
	v_mfma_f32_16x16x32_bf16 v[120:123], v[140:143], v[164:167], v[120:123]
	v_mfma_f32_16x16x32_bf16 v[108:111], v[132:135], v[172:175], v[108:111]
	v_mfma_f32_16x16x32_bf16 v[104:107], v[140:143], v[172:175], v[104:107]
	v_mfma_f32_16x16x32_bf16 v[92:95], v[132:135], v[196:199], v[92:95]
	v_mfma_f32_16x16x32_bf16 v[88:91], v[140:143], v[196:199], v[88:91]
	v_mfma_f32_16x16x32_bf16 v[76:79], v[132:135], v[212:215], v[76:79]
	v_mfma_f32_16x16x32_bf16 v[72:75], v[140:143], v[212:215], v[72:75]
	s_setprio 0
	s_setprio 1
	v_mfma_f32_16x16x32_bf16 v[116:119], v[144:147], v[160:163], v[116:119]
	v_mfma_f32_16x16x32_bf16 v[112:115], v[152:155], v[160:163], v[112:115]
	v_mfma_f32_16x16x32_bf16 v[100:103], v[144:147], v[168:171], v[100:103]
	v_mfma_f32_16x16x32_bf16 v[96:99], v[152:155], v[168:171], v[96:99]
	v_mfma_f32_16x16x32_bf16 v[84:87], v[144:147], v[192:195], v[84:87]
	v_mfma_f32_16x16x32_bf16 v[80:83], v[152:155], v[192:195], v[80:83]
	v_mfma_f32_16x16x32_bf16 v[68:71], v[144:147], v[200:203], v[68:71]
	v_mfma_f32_16x16x32_bf16 v[64:67], v[152:155], v[200:203], v[64:67]
	v_mfma_f32_16x16x32_bf16 v[116:119], v[148:151], v[164:167], v[116:119]
	v_mfma_f32_16x16x32_bf16 v[112:115], v[156:159], v[164:167], v[112:115]
	v_mfma_f32_16x16x32_bf16 v[100:103], v[148:151], v[172:175], v[100:103]
	v_mfma_f32_16x16x32_bf16 v[96:99], v[156:159], v[172:175], v[96:99]
	v_mfma_f32_16x16x32_bf16 v[84:87], v[148:151], v[196:199], v[84:87]
	v_mfma_f32_16x16x32_bf16 v[80:83], v[156:159], v[196:199], v[80:83]
	v_mfma_f32_16x16x32_bf16 v[68:71], v[148:151], v[212:215], v[68:71]
	v_mfma_f32_16x16x32_bf16 v[64:67], v[156:159], v[212:215], v[64:67]
	s_setprio 0
	s_barrier
	s_add_i32 s24, s49, s0
	s_mov_b32 m0, s24
	ds_read_b128 v[160:163], v210 offset:49152
	ds_read_b128 v[164:167], v210 offset:50176
	ds_read_b128 v[168:171], v210 offset:51200
	ds_read_b128 v[172:175], v210 offset:52224
	global_load_lds_dwordx4 v178, vcc
	s_add_i32 m0, s24, 0x2000
	s_add_u32 s22, s22, 0x160080
	s_addc_u32 s23, s23, 0
	s_add_i32 s24, s50, s0
	global_load_lds_dwordx4 v182, vcc
	s_mov_b32 m0, s24
	ds_read_b128 v[212:215], v210 offset:56320
	global_load_lds_dwordx4 v178, s[22:23]
	s_add_i32 m0, s24, 0x2000
	ds_read_b128 v[200:203], v210 offset:55296
	global_load_lds_dwordx4 v182, s[22:23]
	s_mov_b32 m0, s30
	ds_read_b128 v[196:199], v210 offset:54272
	global_load_lds_dwordx4 v176, s[98:99]
	s_mov_b32 m0, s31
	ds_read_b128 v[192:195], v210 offset:53248
	global_load_lds_dwordx4 v180, s[98:99]
	s_waitcnt vmcnt(8) lgkmcnt(0)
	s_barrier
	s_setprio 1
	v_mfma_f32_16x16x32_bf16 v[60:63], v[128:131], v[160:163], v[60:63]
	v_mfma_f32_16x16x32_bf16 v[56:59], v[136:139], v[160:163], v[56:59]
	v_mfma_f32_16x16x32_bf16 v[44:47], v[128:131], v[168:171], v[44:47]
	v_mfma_f32_16x16x32_bf16 v[40:43], v[136:139], v[168:171], v[40:43]
	v_mfma_f32_16x16x32_bf16 v[28:31], v[128:131], v[192:195], v[28:31]
	v_mfma_f32_16x16x32_bf16 v[24:27], v[136:139], v[192:195], v[24:27]
	v_mfma_f32_16x16x32_bf16 v[12:15], v[128:131], v[200:203], v[12:15]
	v_mfma_f32_16x16x32_bf16 v[8:11], v[136:139], v[200:203], v[8:11]
	v_mfma_f32_16x16x32_bf16 v[60:63], v[132:135], v[164:167], v[60:63]
	v_mfma_f32_16x16x32_bf16 v[56:59], v[140:143], v[164:167], v[56:59]
	v_mfma_f32_16x16x32_bf16 v[44:47], v[132:135], v[172:175], v[44:47]
	v_mfma_f32_16x16x32_bf16 v[40:43], v[140:143], v[172:175], v[40:43]
	v_mfma_f32_16x16x32_bf16 v[28:31], v[132:135], v[196:199], v[28:31]
	v_mfma_f32_16x16x32_bf16 v[24:27], v[140:143], v[196:199], v[24:27]
	v_mfma_f32_16x16x32_bf16 v[12:15], v[132:135], v[212:215], v[12:15]
	v_mfma_f32_16x16x32_bf16 v[8:11], v[140:143], v[212:215], v[8:11]
	s_setprio 0
	s_setprio 1
	v_mfma_f32_16x16x32_bf16 v[52:55], v[144:147], v[160:163], v[52:55]
	v_mfma_f32_16x16x32_bf16 v[48:51], v[152:155], v[160:163], v[48:51]
	v_mfma_f32_16x16x32_bf16 v[36:39], v[144:147], v[168:171], v[36:39]
	v_mfma_f32_16x16x32_bf16 v[32:35], v[152:155], v[168:171], v[32:35]
	v_mfma_f32_16x16x32_bf16 v[20:23], v[144:147], v[192:195], v[20:23]
	v_mfma_f32_16x16x32_bf16 v[16:19], v[152:155], v[192:195], v[16:19]
	v_mfma_f32_16x16x32_bf16 v[4:7], v[144:147], v[200:203], v[4:7]
	v_mfma_f32_16x16x32_bf16 v[0:3], v[152:155], v[200:203], v[0:3]
	v_mfma_f32_16x16x32_bf16 v[52:55], v[148:151], v[164:167], v[52:55]
	v_mfma_f32_16x16x32_bf16 v[48:51], v[156:159], v[164:167], v[48:51]
	v_mfma_f32_16x16x32_bf16 v[36:39], v[148:151], v[172:175], v[36:39]
	v_mfma_f32_16x16x32_bf16 v[32:35], v[156:159], v[172:175], v[32:35]
	v_mfma_f32_16x16x32_bf16 v[20:23], v[148:151], v[196:199], v[20:23]
	v_mfma_f32_16x16x32_bf16 v[16:19], v[156:159], v[196:199], v[16:19]
	v_mfma_f32_16x16x32_bf16 v[4:7], v[148:151], v[212:215], v[4:7]
	v_mfma_f32_16x16x32_bf16 v[0:3], v[156:159], v[212:215], v[0:3]
	s_setprio 0
	s_barrier
	s_add_i32 s48, s48, 2
	s_add_u32 s20, s20, 0x100
	s_addc_u32 s21, s21, 0
	s_add_u32 s46, s46, 0x100
	s_addc_u32 s47, s47, 0
	s_cmpk_gt_u32 s48, 0x55
	s_cbranch_scc0 .LBB0_285
	s_and_b64 vcc, exec, s[16:17]
	s_cbranch_vccz .LBB0_288
	s_barrier

; #define PG8_STAGE(bufoff, gbase, voff) do { _Pragma("unroll") for (int _i = 0; _i < 2; ++_i) \
;         __builtin_amdgcn_global_load_lds((const unsigned*)((const char*)(gbase) + (voff)[_i]), (PG8_LAS unsigned*)(lds + (bufoff) + ldsw + _i * 8192), 16, 0, 0); } while (0)
; #define PG8_LDA(dst, b, h) do { _Pragma("unroll") for (int m = 0; m < 4; ++m) _Pragma("unroll") for (int k = 0; k < 2; ++k) dst[m][k] = *(const PG8_LAS bf16x8*)(lds + PG8_SA(b, h) + aoff + m * 2048 + k * 1024); } while (0)
; #define PG8_MMA(ai, bj, At, Bt) do { __builtin_amdgcn_s_setprio(1); _Pragma("unroll") for (int m = 0; m < 4; ++m) _Pragma("unroll") for (int n = 0; n < 2; ++n) _Pragma("unroll") for (int k = 0; k < 2; ++k) \
;         acc[ai][bj][m][n] = __builtin_amdgcn_mfma_f32_16x16x32_bf16(Bt[n][k], At[m][k], acc[ai][bj][m][n], 0, 0, 0); __builtin_amdgcn_s_setprio(0); } while (0)
; #define PG8_WAIT_V(n) asm volatile("s_waitcnt vmcnt(" #n ")" ::: "memory")
; #define PG8_WAIT_L(n) asm volatile("s_waitcnt lgkmcnt(" #n ")" ::: "memory")
; #define PG8_BAR __builtin_amdgcn_s_barrier()
; #define PG8_SCHED __builtin_amdgcn_sched_barrier(0)
; template <class Epi, class Sched, bool ALIGN_EPI = false, bool SP2 = false>
; __device__ __forceinline__ void gemm_phase(PG8_LAS unsigned char* lds, const Gemm g, const Sched& S, const Epi& E) {
;     ...
;             PG8_WAIT_V(8); PG8_WAIT_L(0); PG8_BAR; PG8_MMA(0, 0, At, B0); PG8_MMA(0, 1, At, B1); PG8_BAR; PG8_SCHED;
;             PG8_LDA(At, 1, 1); PG8_STAGE(PG8_SB(1, 0), b3, voffB); PG8_STAGE(PG8_SB(1, 1), b3 + hstep, voffB); PG8_STAGE(PG8_SA(1, 0), a3, voffA);
;             PG8_WAIT_V(8); PG8_WAIT_L(0); PG8_BAR; PG8_MMA(1, 0, At, B0); PG8_MMA(1, 1, At, B1); PG8_BAR; PG8_SCHED;
;     ...
;         if constexpr (ALIGN_EPI) { if (wr == 0) PG8_BAR; }
.Lgr_p3_2:
	s_waitcnt lgkmcnt(0)
	s_barrier
	s_setprio 1
	v_mfma_f32_16x16x32_bf16 v[124:127], v[128:131], v[190:193], v[124:127]
	v_mfma_f32_16x16x32_bf16 v[120:123], v[156:159], v[190:193], v[120:123]
	v_mfma_f32_16x16x32_bf16 v[108:111], v[128:131], v[198:201], v[108:111]
	v_mfma_f32_16x16x32_bf16 v[104:107], v[156:159], v[198:201], v[104:107]
	v_mfma_f32_16x16x32_bf16 v[92:95], v[128:131], v[210:213], v[92:95]
	v_mfma_f32_16x16x32_bf16 v[88:91], v[156:159], v[210:213], v[88:91]
	v_mfma_f32_16x16x32_bf16 v[76:79], v[128:131], v[222:225], v[76:79]
	v_mfma_f32_16x16x32_bf16 v[72:75], v[156:159], v[222:225], v[72:75]
	v_mfma_f32_16x16x32_bf16 v[124:127], v[132:135], v[194:197], v[124:127]
	v_mfma_f32_16x16x32_bf16 v[120:123], v[160:163], v[194:197], v[120:123]
	v_mfma_f32_16x16x32_bf16 v[108:111], v[132:135], v[206:209], v[108:111]
	v_mfma_f32_16x16x32_bf16 v[104:107], v[160:163], v[206:209], v[104:107]
	v_mfma_f32_16x16x32_bf16 v[92:95], v[132:135], v[214:217], v[92:95]
	v_mfma_f32_16x16x32_bf16 v[88:91], v[160:163], v[214:217], v[88:91]
	v_mfma_f32_16x16x32_bf16 v[76:79], v[132:135], v[226:229], v[76:79]
	v_mfma_f32_16x16x32_bf16 v[72:75], v[160:163], v[226:229], v[72:75]
	s_setprio 0
	s_setprio 1
	v_mfma_f32_16x16x32_bf16 v[116:119], v[164:167], v[190:193], v[116:119]
	v_mfma_f32_16x16x32_bf16 v[112:115], v[182:185], v[190:193], v[112:115]
	v_mfma_f32_16x16x32_bf16 v[100:103], v[164:167], v[198:201], v[100:103]
	v_mfma_f32_16x16x32_bf16 v[96:99], v[182:185], v[198:201], v[96:99]
	v_mfma_f32_16x16x32_bf16 v[84:87], v[164:167], v[210:213], v[84:87]
	v_mfma_f32_16x16x32_bf16 v[80:83], v[182:185], v[210:213], v[80:83]
	v_mfma_f32_16x16x32_bf16 v[68:71], v[164:167], v[222:225], v[68:71]
	v_mfma_f32_16x16x32_bf16 v[64:67], v[182:185], v[222:225], v[64:67]
	v_mfma_f32_16x16x32_bf16 v[116:119], v[178:181], v[194:197], v[116:119]
	v_mfma_f32_16x16x32_bf16 v[112:115], v[186:189], v[194:197], v[112:115]
	v_mfma_f32_16x16x32_bf16 v[100:103], v[178:181], v[206:209], v[100:103]
	v_mfma_f32_16x16x32_bf16 v[96:99], v[186:189], v[206:209], v[96:99]
	v_mfma_f32_16x16x32_bf16 v[84:87], v[178:181], v[214:217], v[84:87]
	v_mfma_f32_16x16x32_bf16 v[80:83], v[186:189], v[214:217], v[80:83]
	v_mfma_f32_16x16x32_bf16 v[68:71], v[178:181], v[226:229], v[68:71]
	v_mfma_f32_16x16x32_bf16 v[64:67], v[186:189], v[226:229], v[64:67]
	s_setprio 0
	s_barrier
	s_add_i32 s42, s69, s0
	s_mov_b32 m0, s42
	ds_read_b128 v[190:193], v175 offset:49152
	ds_read_b128 v[194:197], v175 offset:50176
	ds_read_b128 v[198:201], v175 offset:51200
	ds_read_b128 v[206:209], v175 offset:52224
	global_load_lds_dwordx4 v138, vcc
	s_add_i32 m0, s42, 0x2000
	s_add_u32 s6, s6, 0x80080
	s_addc_u32 s7, s7, 0
	s_add_i32 s42, s70, s0
	global_load_lds_dwordx4 v142, vcc
	s_mov_b32 m0, s42
	ds_read_b128 v[226:229], v175 offset:56320
	global_load_lds_dwordx4 v138, s[6:7]
	s_add_i32 m0, s42, 0x2000
	ds_read_b128 v[222:225], v175 offset:55296
	global_load_lds_dwordx4 v142, s[6:7]
	s_mov_b32 m0, s48
	ds_read_b128 v[214:217], v175 offset:54272
	global_load_lds_dwordx4 v136, s[98:99]
	s_mov_b32 m0, s49
	ds_read_b128 v[210:213], v175 offset:53248
	global_load_lds_dwordx4 v140, s[98:99]
	s_waitcnt vmcnt(8) lgkmcnt(0)
	s_barrier
	s_setprio 1
	v_mfma_f32_16x16x32_bf16 v[60:63], v[128:131], v[190:193], v[60:63]
	v_mfma_f32_16x16x32_bf16 v[56:59], v[156:159], v[190:193], v[56:59]
	v_mfma_f32_16x16x32_bf16 v[44:47], v[128:131], v[198:201], v[44:47]
	v_mfma_f32_16x16x32_bf16 v[40:43], v[156:159], v[198:201], v[40:43]
	v_mfma_f32_16x16x32_bf16 v[28:31], v[128:131], v[210:213], v[28:31]
	v_mfma_f32_16x16x32_bf16 v[24:27], v[156:159], v[210:213], v[24:27]
	v_mfma_f32_16x16x32_bf16 v[12:15], v[128:131], v[222:225], v[12:15]
	v_mfma_f32_16x16x32_bf16 v[8:11], v[156:159], v[222:225], v[8:11]
	v_mfma_f32_16x16x32_bf16 v[60:63], v[132:135], v[194:197], v[60:63]
	v_mfma_f32_16x16x32_bf16 v[56:59], v[160:163], v[194:197], v[56:59]
	v_mfma_f32_16x16x32_bf16 v[44:47], v[132:135], v[206:209], v[44:47]
	v_mfma_f32_16x16x32_bf16 v[40:43], v[160:163], v[206:209], v[40:43]
	v_mfma_f32_16x16x32_bf16 v[28:31], v[132:135], v[214:217], v[28:31]
	v_mfma_f32_16x16x32_bf16 v[24:27], v[160:163], v[214:217], v[24:27]
	v_mfma_f32_16x16x32_bf16 v[12:15], v[132:135], v[226:229], v[12:15]
	v_mfma_f32_16x16x32_bf16 v[8:11], v[160:163], v[226:229], v[8:11]
	s_setprio 0
	s_setprio 1
	v_mfma_f32_16x16x32_bf16 v[52:55], v[164:167], v[190:193], v[52:55]
	v_mfma_f32_16x16x32_bf16 v[48:51], v[182:185], v[190:193], v[48:51]
	v_mfma_f32_16x16x32_bf16 v[36:39], v[164:167], v[198:201], v[36:39]
	v_mfma_f32_16x16x32_bf16 v[32:35], v[182:185], v[198:201], v[32:35]
	v_mfma_f32_16x16x32_bf16 v[20:23], v[164:167], v[210:213], v[20:23]
	v_mfma_f32_16x16x32_bf16 v[16:19], v[182:185], v[210:213], v[16:19]
	v_mfma_f32_16x16x32_bf16 v[4:7], v[164:167], v[222:225], v[4:7]
	v_mfma_f32_16x16x32_bf16 v[0:3], v[182:185], v[222:225], v[0:3]
	v_mfma_f32_16x16x32_bf16 v[52:55], v[178:181], v[194:197], v[52:55]
	v_mfma_f32_16x16x32_bf16 v[48:51], v[186:189], v[194:197], v[48:51]
	v_mfma_f32_16x16x32_bf16 v[36:39], v[178:181], v[206:209], v[36:39]
	v_mfma_f32_16x16x32_bf16 v[32:35], v[186:189], v[206:209], v[32:35]
	v_mfma_f32_16x16x32_bf16 v[20:23], v[178:181], v[214:217], v[20:23]
	v_mfma_f32_16x16x32_bf16 v[16:19], v[186:189], v[214:217], v[16:19]
	v_mfma_f32_16x16x32_bf16 v[4:7], v[178:181], v[226:229], v[4:7]
	v_mfma_f32_16x16x32_bf16 v[0:3], v[186:189], v[226:229], v[0:3]
	s_setprio 0
	s_barrier
	s_mov_b32 s100, 0
	s_add_i32 s47, s47, 2
	s_add_u32 s4, s4, 0x100
	s_addc_u32 s5, s5, 0
	s_add_u32 s45, s45, 0x100
	s_addc_u32 s46, s46, 0
	s_cmp_gt_u32 s47, 29
	s_cbranch_scc0 .LBB0_370
	s_and_b64 vcc, exec, s[18:19]
	s_cbranch_vccnz .LBB0_375
	s_add_u32 s98, s29, 0x80080
	s_addc_u32 s99, s10, 0
	v_lshl_add_u64 v[252:253], s[98:99], 0, v[146:147]
	s_add_i32 m0, s1, 0xc000
	s_nop 0
	global_load_lds_dwordx4 v[252:253], off
	v_lshl_add_u64 v[252:253], s[98:99], 0, v[148:149]
	s_add_i32 m0, s1, 0xe000
	s_nop 0
	global_load_lds_dwordx4 v[252:253], off
	s_mov_b32 s100, 1
	s_cmp_gt_i32 s36, 7
	s_mov_b64 s[4:5], -1
	s_cbranch_scc1 .LBB0_376

; #define PG8_STAGE(bufoff, gbase, voff) do { _Pragma("unroll") for (int _i = 0; _i < 2; ++_i) \
;         __builtin_amdgcn_global_load_lds((const unsigned*)((const char*)(gbase) + (voff)[_i]), (PG8_LAS unsigned*)(lds + (bufoff) + ldsw + _i * 8192), 16, 0, 0); } while (0)
; #define PG8_LDA(dst, b, h) do { _Pragma("unroll") for (int m = 0; m < 4; ++m) _Pragma("unroll") for (int k = 0; k < 2; ++k) dst[m][k] = *(const PG8_LAS bf16x8*)(lds + PG8_SA(b, h) + aoff + m * 2048 + k * 1024); } while (0)
; #define PG8_MMA(ai, bj, At, Bt) do { __builtin_amdgcn_s_setprio(1); _Pragma("unroll") for (int m = 0; m < 4; ++m) _Pragma("unroll") for (int n = 0; n < 2; ++n) _Pragma("unroll") for (int k = 0; k < 2; ++k) \
;         acc[ai][bj][m][n] = __builtin_amdgcn_mfma_f32_16x16x32_bf16(Bt[n][k], At[m][k], acc[ai][bj][m][n], 0, 0, 0); __builtin_amdgcn_s_setprio(0); } while (0)
; #define PG8_WAIT_V(n) asm volatile("s_waitcnt vmcnt(" #n ")" ::: "memory")
; #define PG8_WAIT_L(n) asm volatile("s_waitcnt lgkmcnt(" #n ")" ::: "memory")
; #define PG8_BAR __builtin_amdgcn_s_barrier()
; #define PG8_SCHED __builtin_amdgcn_sched_barrier(0)
; template <class Epi, class Sched, bool ALIGN_EPI = false, bool SP2 = false>
; __device__ __forceinline__ void gemm_phase(PG8_LAS unsigned char* lds, const Gemm g, const Sched& S, const Epi& E) {
;     ...
;             PG8_WAIT_V(8); PG8_WAIT_L(0); PG8_BAR; PG8_MMA(0, 0, At, B0); PG8_MMA(0, 1, At, B1); PG8_BAR; PG8_SCHED;
;             PG8_LDA(At, 1, 1); PG8_STAGE(PG8_SB(1, 0), b3, voffB); PG8_STAGE(PG8_SB(1, 1), b3 + hstep, voffB); PG8_STAGE(PG8_SA(1, 0), a3, voffA);
;             PG8_WAIT_V(8); PG8_WAIT_L(0); PG8_BAR; PG8_MMA(1, 0, At, B0); PG8_MMA(1, 1, At, B1); PG8_BAR; PG8_SCHED;
;     ...
;         if constexpr (ALIGN_EPI) { if (wr == 0) PG8_BAR; }
.Lgr_p5_2:
	s_waitcnt lgkmcnt(0)
	s_barrier
	s_setprio 1
	v_mfma_f32_16x16x32_bf16 v[124:127], v[128:131], v[160:163], v[124:127]
	v_mfma_f32_16x16x32_bf16 v[120:123], v[136:139], v[160:163], v[120:123]
	v_mfma_f32_16x16x32_bf16 v[108:111], v[128:131], v[168:171], v[108:111]
	v_mfma_f32_16x16x32_bf16 v[104:107], v[136:139], v[168:171], v[104:107]
	v_mfma_f32_16x16x32_bf16 v[92:95], v[128:131], v[176:179], v[92:95]
	v_mfma_f32_16x16x32_bf16 v[88:91], v[136:139], v[176:179], v[88:91]
	v_mfma_f32_16x16x32_bf16 v[76:79], v[128:131], v[184:187], v[76:79]
	v_mfma_f32_16x16x32_bf16 v[72:75], v[136:139], v[184:187], v[72:75]
	v_mfma_f32_16x16x32_bf16 v[124:127], v[132:135], v[164:167], v[124:127]
	v_mfma_f32_16x16x32_bf16 v[120:123], v[140:143], v[164:167], v[120:123]
	v_mfma_f32_16x16x32_bf16 v[108:111], v[132:135], v[172:175], v[108:111]
	v_mfma_f32_16x16x32_bf16 v[104:107], v[140:143], v[172:175], v[104:107]
	v_mfma_f32_16x16x32_bf16 v[92:95], v[132:135], v[180:183], v[92:95]
	v_mfma_f32_16x16x32_bf16 v[88:91], v[140:143], v[180:183], v[88:91]
	v_mfma_f32_16x16x32_bf16 v[76:79], v[132:135], v[188:191], v[76:79]
	v_mfma_f32_16x16x32_bf16 v[72:75], v[140:143], v[188:191], v[72:75]
	s_setprio 0
	s_setprio 1
	v_mfma_f32_16x16x32_bf16 v[116:119], v[144:147], v[160:163], v[116:119]
	v_mfma_f32_16x16x32_bf16 v[112:115], v[152:155], v[160:163], v[112:115]
	v_mfma_f32_16x16x32_bf16 v[100:103], v[144:147], v[168:171], v[100:103]
	v_mfma_f32_16x16x32_bf16 v[96:99], v[152:155], v[168:171], v[96:99]
	v_mfma_f32_16x16x32_bf16 v[84:87], v[144:147], v[176:179], v[84:87]
	v_mfma_f32_16x16x32_bf16 v[80:83], v[152:155], v[176:179], v[80:83]
	v_mfma_f32_16x16x32_bf16 v[68:71], v[144:147], v[184:187], v[68:71]
	v_mfma_f32_16x16x32_bf16 v[64:67], v[152:155], v[184:187], v[64:67]
	v_mfma_f32_16x16x32_bf16 v[116:119], v[148:151], v[164:167], v[116:119]
	v_mfma_f32_16x16x32_bf16 v[112:115], v[156:159], v[164:167], v[112:115]
	v_mfma_f32_16x16x32_bf16 v[100:103], v[148:151], v[172:175], v[100:103]
	v_mfma_f32_16x16x32_bf16 v[96:99], v[156:159], v[172:175], v[96:99]
	v_mfma_f32_16x16x32_bf16 v[84:87], v[148:151], v[180:183], v[84:87]
	v_mfma_f32_16x16x32_bf16 v[80:83], v[156:159], v[180:183], v[80:83]
	v_mfma_f32_16x16x32_bf16 v[68:71], v[148:151], v[188:191], v[68:71]
	v_mfma_f32_16x16x32_bf16 v[64:67], v[156:159], v[188:191], v[64:67]
	s_setprio 0
	s_barrier
	s_add_i32 s26, s47, s29
	s_mov_b32 m0, s26
	ds_read_b128 v[160:163], v226 offset:49152
	ds_read_b128 v[164:167], v226 offset:50176
	ds_read_b128 v[168:171], v226 offset:51200
	ds_read_b128 v[172:175], v226 offset:52224
	global_load_lds_dwordx4 v194, vcc
	s_add_i32 m0, s26, 0x2000
	s_add_u32 s24, s24, 0x40080
	s_addc_u32 s25, s25, 0
	s_add_i32 s26, s48, s29
	global_load_lds_dwordx4 v198, vcc
	s_mov_b32 m0, s26
	ds_read_b128 v[188:191], v226 offset:56320
	global_load_lds_dwordx4 v194, s[24:25]
	s_add_i32 m0, s26, 0x2000
	ds_read_b128 v[184:187], v226 offset:55296
	global_load_lds_dwordx4 v198, s[24:25]
	s_mov_b32 m0, s37
	ds_read_b128 v[180:183], v226 offset:54272
	global_load_lds_dwordx4 v192, s[98:99]
	s_mov_b32 m0, s38
	ds_read_b128 v[176:179], v226 offset:53248
	global_load_lds_dwordx4 v196, s[98:99]
	s_waitcnt vmcnt(8) lgkmcnt(0)
	s_barrier
	s_setprio 1
	v_mfma_f32_16x16x32_bf16 v[60:63], v[128:131], v[160:163], v[60:63]
	v_mfma_f32_16x16x32_bf16 v[56:59], v[136:139], v[160:163], v[56:59]
	v_mfma_f32_16x16x32_bf16 v[44:47], v[128:131], v[168:171], v[44:47]
	v_mfma_f32_16x16x32_bf16 v[40:43], v[136:139], v[168:171], v[40:43]
	v_mfma_f32_16x16x32_bf16 v[28:31], v[128:131], v[176:179], v[28:31]
	v_mfma_f32_16x16x32_bf16 v[24:27], v[136:139], v[176:179], v[24:27]
	v_mfma_f32_16x16x32_bf16 v[12:15], v[128:131], v[184:187], v[12:15]
	v_mfma_f32_16x16x32_bf16 v[8:11], v[136:139], v[184:187], v[8:11]
	v_mfma_f32_16x16x32_bf16 v[60:63], v[132:135], v[164:167], v[60:63]
	v_mfma_f32_16x16x32_bf16 v[56:59], v[140:143], v[164:167], v[56:59]
	v_mfma_f32_16x16x32_bf16 v[44:47], v[132:135], v[172:175], v[44:47]
	v_mfma_f32_16x16x32_bf16 v[40:43], v[140:143], v[172:175], v[40:43]
	v_mfma_f32_16x16x32_bf16 v[28:31], v[132:135], v[180:183], v[28:31]
	v_mfma_f32_16x16x32_bf16 v[24:27], v[140:143], v[180:183], v[24:27]
	v_mfma_f32_16x16x32_bf16 v[12:15], v[132:135], v[188:191], v[12:15]
	v_mfma_f32_16x16x32_bf16 v[8:11], v[140:143], v[188:191], v[8:11]
	s_setprio 0
	s_setprio 1
	v_mfma_f32_16x16x32_bf16 v[52:55], v[144:147], v[160:163], v[52:55]
	v_mfma_f32_16x16x32_bf16 v[48:51], v[152:155], v[160:163], v[48:51]
	v_mfma_f32_16x16x32_bf16 v[36:39], v[144:147], v[168:171], v[36:39]
	v_mfma_f32_16x16x32_bf16 v[32:35], v[152:155], v[168:171], v[32:35]
	v_mfma_f32_16x16x32_bf16 v[20:23], v[144:147], v[176:179], v[20:23]
	v_mfma_f32_16x16x32_bf16 v[16:19], v[152:155], v[176:179], v[16:19]
	v_mfma_f32_16x16x32_bf16 v[4:7], v[144:147], v[184:187], v[4:7]
	v_mfma_f32_16x16x32_bf16 v[0:3], v[152:155], v[184:187], v[0:3]
	v_mfma_f32_16x16x32_bf16 v[52:55], v[148:151], v[164:167], v[52:55]
	v_mfma_f32_16x16x32_bf16 v[48:51], v[156:159], v[164:167], v[48:51]
	v_mfma_f32_16x16x32_bf16 v[36:39], v[148:151], v[172:175], v[36:39]
	v_mfma_f32_16x16x32_bf16 v[32:35], v[156:159], v[172:175], v[32:35]
	v_mfma_f32_16x16x32_bf16 v[20:23], v[148:151], v[180:183], v[20:23]
	v_mfma_f32_16x16x32_bf16 v[16:19], v[156:159], v[180:183], v[16:19]
	v_mfma_f32_16x16x32_bf16 v[4:7], v[148:151], v[188:191], v[4:7]
	v_mfma_f32_16x16x32_bf16 v[0:3], v[156:159], v[188:191], v[0:3]
	s_setprio 0
	s_barrier
	s_mov_b32 s100, 0
	s_add_i32 s46, s46, 2
	s_add_u32 s0, s0, 0x100
	s_addc_u32 s1, s1, 0
	s_add_u32 s44, s44, 0x100
	s_addc_u32 s45, s45, 0
	s_cmp_gt_u32 s46, 13
	s_cbranch_scc0 .LBB0_884
	s_and_b64 vcc, exec, s[8:9]
	s_cbranch_vccz .LBB0_887
	s_barrier

; #define PG8_STAGE(bufoff, gbase, voff) do { _Pragma("unroll") for (int _i = 0; _i < 2; ++_i) \
;         __builtin_amdgcn_global_load_lds((const unsigned*)((const char*)(gbase) + (voff)[_i]), (PG8_LAS unsigned*)(lds + (bufoff) + ldsw + _i * 8192), 16, 0, 0); } while (0)
; #define PG8_LDA(dst, b, h) do { _Pragma("unroll") for (int m = 0; m < 4; ++m) _Pragma("unroll") for (int k = 0; k < 2; ++k) dst[m][k] = *(const PG8_LAS bf16x8*)(lds + PG8_SA(b, h) + aoff + m * 2048 + k * 1024); } while (0)
; #define PG8_LDB(dst, b, h) do { _Pragma("unroll") for (int n = 0; n < 2; ++n) _Pragma("unroll") for (int k = 0; k < 2; ++k) dst[n][k] = *(const PG8_LAS bf16x8*)(lds + PG8_SB(b, h) + boff + n * 2048 + k * 1024); } while (0)
; #define PG8_MMA(ai, bj, At, Bt) do { __builtin_amdgcn_s_setprio(1); _Pragma("unroll") for (int m = 0; m < 4; ++m) _Pragma("unroll") for (int n = 0; n < 2; ++n) _Pragma("unroll") for (int k = 0; k < 2; ++k) \
;         acc[ai][bj][m][n] = __builtin_amdgcn_mfma_f32_16x16x32_bf16(Bt[n][k], At[m][k], acc[ai][bj][m][n], 0, 0, 0); __builtin_amdgcn_s_setprio(0); } while (0)
; #define PG8_WAIT_V(n) asm volatile("s_waitcnt vmcnt(" #n ")" ::: "memory")
; #define PG8_WAIT_L(n) asm volatile("s_waitcnt lgkmcnt(" #n ")" ::: "memory")
; template <class Epi, class Sched, bool ALIGN_EPI = false, bool SP2 = false>
; __device__ __forceinline__ void gemm_phase(PG8_LAS unsigned char* lds, const Gemm g, const Sched& S, const Epi& E) {
;     ...
;             const bool last = (t == nt - 2);
;             const char* a1 = cA + (size_t)(t + 1) * kstep;
;             const char* a2 = last ? nA : cA + (size_t)(t + 2) * kstep; const char* b2 = last ? nB : cB + (size_t)(t + 2) * kstep;
;             const char* a3 = a2 + kstep; const char* b3 = b2 + kstep;
;             if (last && has_next) S.a_ready(nxt);
;             if constexpr (SP2) {
;             PG8_LDB(B0, 0, 0); PG8_LDB(B1, 0, 1); PG8_SCHED; PG8_LDA(At, 0, 0); PG8_STAGE(PG8_SA(1, 1), a1 + hstep, voffA);
;             PG8_WAIT_V(8); PG8_WAIT_L(0); PG8_BAR; PG8_MMA(0, 0, At, B0); PG8_MMA(0, 1, At, B1); PG8_BAR; PG8_SCHED;
;             PG8_LDA(At, 0, 1); PG8_STAGE(PG8_SB(0, 0), b2, voffB); PG8_STAGE(PG8_SB(0, 1), b2 + hstep, voffB); PG8_STAGE(PG8_SA(0, 0), a2, voffA);
;             PG8_WAIT_V(8); PG8_WAIT_L(0); PG8_BAR; PG8_MMA(1, 0, At, B0); PG8_MMA(1, 1, At, B1); PG8_BAR; PG8_SCHED;
.LBB0_993:
	ds_read_b128 v[128:131], v213
	ds_read_b128 v[132:135], v213 offset:1024
	ds_read_b128 v[136:139], v213 offset:2048
	ds_read_b128 v[140:143], v213 offset:3072
	ds_read_b128 v[144:147], v214
	ds_read_b128 v[148:151], v214 offset:1024
	ds_read_b128 v[152:155], v214 offset:2048
	ds_read_b128 v[156:159], v214 offset:3072
	s_add_u32 s28, s26, 0xfff80080
	s_addc_u32 s29, s27, -1
	s_cmp_eq_u32 s48, 28
	s_cselect_b32 s31, s17, s29
	s_cselect_b32 s30, s23, s28
	s_cselect_b32 s29, s15, s47
	s_cselect_b32 s28, s45, s46
	s_add_i32 m0, s25, 0xc000
	ds_read_b128 v[160:163], v215
	ds_read_b128 v[164:167], v215 offset:1024
	ds_read_b128 v[168:171], v215 offset:2048
	ds_read_b128 v[172:175], v215 offset:3072
	ds_read_b128 v[192:195], v215 offset:4096
	ds_read_b128 v[196:199], v215 offset:5120
	ds_read_b128 v[200:203], v215 offset:6144
	global_load_lds_dwordx4 v184, s[26:27]
	s_add_i32 m0, s25, 0xe000
	ds_read_b128 v[204:207], v215 offset:7168
	global_load_lds_dwordx4 v186, s[26:27]
	s_waitcnt vmcnt(8) lgkmcnt(0)
	s_barrier
	s_setprio 1
	v_mfma_f32_16x16x32_bf16 v[124:127], v[128:131], v[160:163], v[124:127]
	v_mfma_f32_16x16x32_bf16 v[120:123], v[136:139], v[160:163], v[120:123]
	v_mfma_f32_16x16x32_bf16 v[108:111], v[128:131], v[168:171], v[108:111]
	v_mfma_f32_16x16x32_bf16 v[104:107], v[136:139], v[168:171], v[104:107]
	v_mfma_f32_16x16x32_bf16 v[92:95], v[128:131], v[192:195], v[92:95]
	v_mfma_f32_16x16x32_bf16 v[88:91], v[136:139], v[192:195], v[88:91]
	v_mfma_f32_16x16x32_bf16 v[76:79], v[128:131], v[200:203], v[76:79]
	v_mfma_f32_16x16x32_bf16 v[72:75], v[136:139], v[200:203], v[72:75]
	v_mfma_f32_16x16x32_bf16 v[124:127], v[132:135], v[164:167], v[124:127]
	v_mfma_f32_16x16x32_bf16 v[120:123], v[140:143], v[164:167], v[120:123]
	v_mfma_f32_16x16x32_bf16 v[108:111], v[132:135], v[172:175], v[108:111]
	v_mfma_f32_16x16x32_bf16 v[104:107], v[140:143], v[172:175], v[104:107]
	v_mfma_f32_16x16x32_bf16 v[92:95], v[132:135], v[196:199], v[92:95]
	v_mfma_f32_16x16x32_bf16 v[88:91], v[140:143], v[196:199], v[88:91]
	v_mfma_f32_16x16x32_bf16 v[76:79], v[132:135], v[204:207], v[76:79]
	v_mfma_f32_16x16x32_bf16 v[72:75], v[140:143], v[204:207], v[72:75]
	s_setprio 0
	s_setprio 1
	v_mfma_f32_16x16x32_bf16 v[116:119], v[144:147], v[160:163], v[116:119]
	v_mfma_f32_16x16x32_bf16 v[112:115], v[152:155], v[160:163], v[112:115]
	v_mfma_f32_16x16x32_bf16 v[100:103], v[144:147], v[168:171], v[100:103]
	v_mfma_f32_16x16x32_bf16 v[96:99], v[152:155], v[168:171], v[96:99]
	v_mfma_f32_16x16x32_bf16 v[84:87], v[144:147], v[192:195], v[84:87]
	v_mfma_f32_16x16x32_bf16 v[80:83], v[152:155], v[192:195], v[80:83]
	v_mfma_f32_16x16x32_bf16 v[68:71], v[144:147], v[200:203], v[68:71]
	v_mfma_f32_16x16x32_bf16 v[64:67], v[152:155], v[200:203], v[64:67]
	v_mfma_f32_16x16x32_bf16 v[116:119], v[148:151], v[164:167], v[116:119]
	v_mfma_f32_16x16x32_bf16 v[112:115], v[156:159], v[164:167], v[112:115]
	v_mfma_f32_16x16x32_bf16 v[100:103], v[148:151], v[172:175], v[100:103]
	v_mfma_f32_16x16x32_bf16 v[96:99], v[156:159], v[172:175], v[96:99]
	v_mfma_f32_16x16x32_bf16 v[84:87], v[148:151], v[196:199], v[84:87]
	v_mfma_f32_16x16x32_bf16 v[80:83], v[156:159], v[196:199], v[80:83]
	v_mfma_f32_16x16x32_bf16 v[68:71], v[148:151], v[204:207], v[68:71]
	v_mfma_f32_16x16x32_bf16 v[64:67], v[156:159], v[204:207], v[64:67]
	s_setprio 0
	s_barrier
	s_add_i32 s49, s43, s33
	s_add_u32 vcc_lo, s28, 0x80
	s_addc_u32 vcc_hi, s29, 0
	s_mov_b32 m0, s49
	ds_read_b128 v[160:163], v215 offset:16384
	ds_read_b128 v[164:167], v215 offset:17408
	ds_read_b128 v[168:171], v215 offset:18432
	ds_read_b128 v[172:175], v215 offset:19456
	global_load_lds_dwordx4 v178, s[28:29]
	s_add_i32 m0, s49, 0x2000
	s_add_u32 s50, s28, 0x80000
	s_addc_u32 s51, s29, 0
	s_add_i32 s49, s44, s33
	global_load_lds_dwordx4 v182, s[28:29]
	s_mov_b32 m0, s49
	ds_read_b128 v[204:207], v215 offset:23552
	global_load_lds_dwordx4 v178, s[50:51]
	s_add_i32 m0, s49, 0x2000
	ds_read_b128 v[200:203], v215 offset:22528
	global_load_lds_dwordx4 v182, s[50:51]
	s_add_u32 s98, s30, 0x80
	s_addc_u32 s99, s31, 0
	s_mov_b32 m0, s25
	ds_read_b128 v[196:199], v215 offset:21504
	global_load_lds_dwordx4 v176, s[30:31]
	s_mov_b32 m0, s34
	ds_read_b128 v[192:195], v215 offset:20480
	global_load_lds_dwordx4 v180, s[30:31]
	s_waitcnt vmcnt(8) lgkmcnt(0)
	s_barrier
	s_setprio 1
	v_mfma_f32_16x16x32_bf16 v[60:63], v[128:131], v[160:163], v[60:63]
	v_mfma_f32_16x16x32_bf16 v[56:59], v[136:139], v[160:163], v[56:59]
	v_mfma_f32_16x16x32_bf16 v[44:47], v[128:131], v[168:171], v[44:47]
	v_mfma_f32_16x16x32_bf16 v[40:43], v[136:139], v[168:171], v[40:43]
	v_mfma_f32_16x16x32_bf16 v[28:31], v[128:131], v[192:195], v[28:31]
	v_mfma_f32_16x16x32_bf16 v[24:27], v[136:139], v[192:195], v[24:27]
	v_mfma_f32_16x16x32_bf16 v[12:15], v[128:131], v[200:203], v[12:15]
	v_mfma_f32_16x16x32_bf16 v[8:11], v[136:139], v[200:203], v[8:11]
	v_mfma_f32_16x16x32_bf16 v[60:63], v[132:135], v[164:167], v[60:63]
	v_mfma_f32_16x16x32_bf16 v[56:59], v[140:143], v[164:167], v[56:59]
	v_mfma_f32_16x16x32_bf16 v[44:47], v[132:135], v[172:175], v[44:47]
	v_mfma_f32_16x16x32_bf16 v[40:43], v[140:143], v[172:175], v[40:43]
	v_mfma_f32_16x16x32_bf16 v[28:31], v[132:135], v[196:199], v[28:31]
	v_mfma_f32_16x16x32_bf16 v[24:27], v[140:143], v[196:199], v[24:27]
	v_mfma_f32_16x16x32_bf16 v[12:15], v[132:135], v[204:207], v[12:15]
	v_mfma_f32_16x16x32_bf16 v[8:11], v[140:143], v[204:207], v[8:11]
	s_setprio 0
	s_setprio 1
	v_mfma_f32_16x16x32_bf16 v[52:55], v[144:147], v[160:163], v[52:55]
	v_mfma_f32_16x16x32_bf16 v[48:51], v[152:155], v[160:163], v[48:51]
	v_mfma_f32_16x16x32_bf16 v[36:39], v[144:147], v[168:171], v[36:39]
	v_mfma_f32_16x16x32_bf16 v[32:35], v[152:155], v[168:171], v[32:35]
	v_mfma_f32_16x16x32_bf16 v[20:23], v[144:147], v[192:195], v[20:23]
	v_mfma_f32_16x16x32_bf16 v[16:19], v[152:155], v[192:195], v[16:19]
	v_mfma_f32_16x16x32_bf16 v[4:7], v[144:147], v[200:203], v[4:7]
	v_mfma_f32_16x16x32_bf16 v[0:3], v[152:155], v[200:203], v[0:3]
	v_mfma_f32_16x16x32_bf16 v[52:55], v[148:151], v[164:167], v[52:55]
	v_mfma_f32_16x16x32_bf16 v[48:51], v[156:159], v[164:167], v[48:51]
	v_mfma_f32_16x16x32_bf16 v[36:39], v[148:151], v[172:175], v[36:39]
	v_mfma_f32_16x16x32_bf16 v[32:35], v[156:159], v[172:175], v[32:35]
	v_mfma_f32_16x16x32_bf16 v[20:23], v[148:151], v[196:199], v[20:23]
	v_mfma_f32_16x16x32_bf16 v[16:19], v[156:159], v[196:199], v[16:19]
	v_mfma_f32_16x16x32_bf16 v[4:7], v[148:151], v[204:207], v[4:7]
	v_mfma_f32_16x16x32_bf16 v[0:3], v[156:159], v[204:207], v[0:3]
	s_setprio 0
	s_barrier
; #define PG8_STAGE(bufoff, gbase, voff) do { _Pragma("unroll") for (int _i = 0; _i < 2; ++_i) \
;         __builtin_amdgcn_global_load_lds((const unsigned*)((const char*)(gbase) + (voff)[_i]), (PG8_LAS unsigned*)(lds + (bufoff) + ldsw + _i * 8192), 16, 0, 0); } while (0)
; #define PG8_LDA(dst, b, h) do { _Pragma("unroll") for (int m = 0; m < 4; ++m) _Pragma("unroll") for (int k = 0; k < 2; ++k) dst[m][k] = *(const PG8_LAS bf16x8*)(lds + PG8_SA(b, h) + aoff + m * 2048 + k * 1024); } while (0)
; #define PG8_LDB(dst, b, h) do { _Pragma("unroll") for (int n = 0; n < 2; ++n) _Pragma("unroll") for (int k = 0; k < 2; ++k) dst[n][k] = *(const PG8_LAS bf16x8*)(lds + PG8_SB(b, h) + boff + n * 2048 + k * 1024); } while (0)
; #define PG8_MMA(ai, bj, At, Bt) do { __builtin_amdgcn_s_setprio(1); _Pragma("unroll") for (int m = 0; m < 4; ++m) _Pragma("unroll") for (int n = 0; n < 2; ++n) _Pragma("unroll") for (int k = 0; k < 2; ++k) \
;         acc[ai][bj][m][n] = __builtin_amdgcn_mfma_f32_16x16x32_bf16(Bt[n][k], At[m][k], acc[ai][bj][m][n], 0, 0, 0); __builtin_amdgcn_s_setprio(0); } while (0)
; #define PG8_WAIT_V(n) asm volatile("s_waitcnt vmcnt(" #n ")" ::: "memory")
; #define PG8_WAIT_L(n) asm volatile("s_waitcnt lgkmcnt(" #n ")" ::: "memory")
; #define PG8_BAR __builtin_amdgcn_s_barrier()
; #define PG8_SCHED __builtin_amdgcn_sched_barrier(0)
; template <class Epi, class Sched, bool ALIGN_EPI = false, bool SP2 = false>
; __device__ __forceinline__ void gemm_phase(PG8_LAS unsigned char* lds, const Gemm g, const Sched& S, const Epi& E) {
;     ...
;             PG8_LDB(B0, 1, 0); PG8_LDB(B1, 1, 1); PG8_SCHED; PG8_LDA(At, 1, 0); PG8_STAGE(PG8_SA(0, 1), a2 + hstep, voffA);
;             PG8_WAIT_V(8); PG8_WAIT_L(0); PG8_BAR; PG8_MMA(0, 0, At, B0); PG8_MMA(0, 1, At, B1); PG8_BAR; PG8_SCHED;
;             PG8_LDA(At, 1, 1); PG8_STAGE(PG8_SB(1, 0), b3, voffB); PG8_STAGE(PG8_SB(1, 1), b3 + hstep, voffB); PG8_STAGE(PG8_SA(1, 0), a3, voffA);
;             PG8_WAIT_V(8); PG8_WAIT_L(0); PG8_BAR; PG8_MMA(1, 0, At, B0); PG8_MMA(1, 1, At, B1); PG8_BAR; PG8_SCHED;
;     ...
;         if constexpr (ALIGN_EPI) { if (wr == 0) PG8_BAR; }
	s_add_i32 s49, 0, 0x18000
	s_add_i32 s50, 0, 0x1c000
	v_add_u32_e32 v140, s49, v211
	v_add_u32_e32 v156, s50, v211
	ds_read_b128 v[128:131], v140
	ds_read_b128 v[132:135], v140 offset:1024
	ds_read_b128 v[136:139], v140 offset:2048
	ds_read_b128 v[140:143], v140 offset:3072
	ds_read_b128 v[144:147], v156
	ds_read_b128 v[148:151], v156 offset:1024
	ds_read_b128 v[152:155], v156 offset:2048
	ds_read_b128 v[156:159], v156 offset:3072
	s_add_u32 s30, s30, 0x80000
	s_addc_u32 s31, s31, 0
	s_mov_b32 m0, s35
	ds_read_b128 v[160:163], v215 offset:32768
	ds_read_b128 v[164:167], v215 offset:33792
	ds_read_b128 v[168:171], v215 offset:34816
	ds_read_b128 v[172:175], v215 offset:35840
	ds_read_b128 v[192:195], v215 offset:36864
	ds_read_b128 v[196:199], v215 offset:37888
	ds_read_b128 v[200:203], v215 offset:38912
	global_load_lds_dwordx4 v176, s[30:31]
	s_mov_b32 m0, s36
	ds_read_b128 v[204:207], v215 offset:39936
	global_load_lds_dwordx4 v180, s[30:31]
	s_waitcnt vmcnt(8) lgkmcnt(0)
	s_barrier
	s_setprio 1
	v_mfma_f32_16x16x32_bf16 v[124:127], v[128:131], v[160:163], v[124:127]
	v_mfma_f32_16x16x32_bf16 v[120:123], v[136:139], v[160:163], v[120:123]
	v_mfma_f32_16x16x32_bf16 v[108:111], v[128:131], v[168:171], v[108:111]
	v_mfma_f32_16x16x32_bf16 v[104:107], v[136:139], v[168:171], v[104:107]
	v_mfma_f32_16x16x32_bf16 v[92:95], v[128:131], v[192:195], v[92:95]
	v_mfma_f32_16x16x32_bf16 v[88:91], v[136:139], v[192:195], v[88:91]
	v_mfma_f32_16x16x32_bf16 v[76:79], v[128:131], v[200:203], v[76:79]
	v_mfma_f32_16x16x32_bf16 v[72:75], v[136:139], v[200:203], v[72:75]
	v_mfma_f32_16x16x32_bf16 v[124:127], v[132:135], v[164:167], v[124:127]
	v_mfma_f32_16x16x32_bf16 v[120:123], v[140:143], v[164:167], v[120:123]
	v_mfma_f32_16x16x32_bf16 v[108:111], v[132:135], v[172:175], v[108:111]
	v_mfma_f32_16x16x32_bf16 v[104:107], v[140:143], v[172:175], v[104:107]
	v_mfma_f32_16x16x32_bf16 v[92:95], v[132:135], v[196:199], v[92:95]
	v_mfma_f32_16x16x32_bf16 v[88:91], v[140:143], v[196:199], v[88:91]
	v_mfma_f32_16x16x32_bf16 v[76:79], v[132:135], v[204:207], v[76:79]
	v_mfma_f32_16x16x32_bf16 v[72:75], v[140:143], v[204:207], v[72:75]
	s_setprio 0
	s_setprio 1
	v_mfma_f32_16x16x32_bf16 v[116:119], v[144:147], v[160:163], v[116:119]
	v_mfma_f32_16x16x32_bf16 v[112:115], v[152:155], v[160:163], v[112:115]
	v_mfma_f32_16x16x32_bf16 v[100:103], v[144:147], v[168:171], v[100:103]
	v_mfma_f32_16x16x32_bf16 v[96:99], v[152:155], v[168:171], v[96:99]
	v_mfma_f32_16x16x32_bf16 v[84:87], v[144:147], v[192:195], v[84:87]
	v_mfma_f32_16x16x32_bf16 v[80:83], v[152:155], v[192:195], v[80:83]
	v_mfma_f32_16x16x32_bf16 v[68:71], v[144:147], v[200:203], v[68:71]
	v_mfma_f32_16x16x32_bf16 v[64:67], v[152:155], v[200:203], v[64:67]
	v_mfma_f32_16x16x32_bf16 v[116:119], v[148:151], v[164:167], v[116:119]
	v_mfma_f32_16x16x32_bf16 v[112:115], v[156:159], v[164:167], v[112:115]
	v_mfma_f32_16x16x32_bf16 v[100:103], v[148:151], v[172:175], v[100:103]
	v_mfma_f32_16x16x32_bf16 v[96:99], v[156:159], v[172:175], v[96:99]
	v_mfma_f32_16x16x32_bf16 v[84:87], v[148:151], v[196:199], v[84:87]
	v_mfma_f32_16x16x32_bf16 v[80:83], v[156:159], v[196:199], v[80:83]
	v_mfma_f32_16x16x32_bf16 v[68:71], v[148:151], v[204:207], v[68:71]
	v_mfma_f32_16x16x32_bf16 v[64:67], v[156:159], v[204:207], v[64:67]
	s_setprio 0
	s_barrier
	s_add_i32 s30, s49, s33
	s_mov_b32 m0, s30
	ds_read_b128 v[160:163], v215 offset:49152
	ds_read_b128 v[164:167], v215 offset:50176
	ds_read_b128 v[168:171], v215 offset:51200
	ds_read_b128 v[172:175], v215 offset:52224
	global_load_lds_dwordx4 v178, vcc
	s_add_i32 m0, s30, 0x2000
	s_add_u32 s28, s28, 0x80080
	s_addc_u32 s29, s29, 0
	s_add_i32 s30, s50, s33
	global_load_lds_dwordx4 v182, vcc
	s_mov_b32 m0, s30
	ds_read_b128 v[204:207], v215 offset:56320
	global_load_lds_dwordx4 v178, s[28:29]
	s_add_i32 m0, s30, 0x2000
	ds_read_b128 v[200:203], v215 offset:55296
	global_load_lds_dwordx4 v182, s[28:29]
	s_mov_b32 m0, s38
	ds_read_b128 v[196:199], v215 offset:54272
	global_load_lds_dwordx4 v176, s[98:99]
	s_mov_b32 m0, s39
	ds_read_b128 v[192:195], v215 offset:53248
	global_load_lds_dwordx4 v180, s[98:99]
	s_waitcnt vmcnt(8) lgkmcnt(0)
	s_barrier
	s_setprio 1
	v_mfma_f32_16x16x32_bf16 v[60:63], v[128:131], v[160:163], v[60:63]
	v_mfma_f32_16x16x32_bf16 v[56:59], v[136:139], v[160:163], v[56:59]
	v_mfma_f32_16x16x32_bf16 v[44:47], v[128:131], v[168:171], v[44:47]
	v_mfma_f32_16x16x32_bf16 v[40:43], v[136:139], v[168:171], v[40:43]
	v_mfma_f32_16x16x32_bf16 v[28:31], v[128:131], v[192:195], v[28:31]
	v_mfma_f32_16x16x32_bf16 v[24:27], v[136:139], v[192:195], v[24:27]
	v_mfma_f32_16x16x32_bf16 v[12:15], v[128:131], v[200:203], v[12:15]
	v_mfma_f32_16x16x32_bf16 v[8:11], v[136:139], v[200:203], v[8:11]
	v_mfma_f32_16x16x32_bf16 v[60:63], v[132:135], v[164:167], v[60:63]
	v_mfma_f32_16x16x32_bf16 v[56:59], v[140:143], v[164:167], v[56:59]
	v_mfma_f32_16x16x32_bf16 v[44:47], v[132:135], v[172:175], v[44:47]
	v_mfma_f32_16x16x32_bf16 v[40:43], v[140:143], v[172:175], v[40:43]
	v_mfma_f32_16x16x32_bf16 v[28:31], v[132:135], v[196:199], v[28:31]
	v_mfma_f32_16x16x32_bf16 v[24:27], v[140:143], v[196:199], v[24:27]
	v_mfma_f32_16x16x32_bf16 v[12:15], v[132:135], v[204:207], v[12:15]
	v_mfma_f32_16x16x32_bf16 v[8:11], v[140:143], v[204:207], v[8:11]
	s_setprio 0
	s_setprio 1
	v_mfma_f32_16x16x32_bf16 v[52:55], v[144:147], v[160:163], v[52:55]
	v_mfma_f32_16x16x32_bf16 v[48:51], v[152:155], v[160:163], v[48:51]
	v_mfma_f32_16x16x32_bf16 v[36:39], v[144:147], v[168:171], v[36:39]
	v_mfma_f32_16x16x32_bf16 v[32:35], v[152:155], v[168:171], v[32:35]
	v_mfma_f32_16x16x32_bf16 v[20:23], v[144:147], v[192:195], v[20:23]
	v_mfma_f32_16x16x32_bf16 v[16:19], v[152:155], v[192:195], v[16:19]
	v_mfma_f32_16x16x32_bf16 v[4:7], v[144:147], v[200:203], v[4:7]
	v_mfma_f32_16x16x32_bf16 v[0:3], v[152:155], v[200:203], v[0:3]
	v_mfma_f32_16x16x32_bf16 v[52:55], v[148:151], v[164:167], v[52:55]
	v_mfma_f32_16x16x32_bf16 v[48:51], v[156:159], v[164:167], v[48:51]
	v_mfma_f32_16x16x32_bf16 v[36:39], v[148:151], v[172:175], v[36:39]
	v_mfma_f32_16x16x32_bf16 v[32:35], v[156:159], v[172:175], v[32:35]
	v_mfma_f32_16x16x32_bf16 v[20:23], v[148:151], v[196:199], v[20:23]
	v_mfma_f32_16x16x32_bf16 v[16:19], v[156:159], v[196:199], v[16:19]
	v_mfma_f32_16x16x32_bf16 v[4:7], v[148:151], v[204:207], v[4:7]
	v_mfma_f32_16x16x32_bf16 v[0:3], v[156:159], v[204:207], v[0:3]
	s_setprio 0
	s_barrier
	s_add_i32 s48, s48, 2
	s_add_u32 s26, s26, 0x100
	s_addc_u32 s27, s27, 0
	s_add_u32 s46, s46, 0x100
	s_addc_u32 s47, s47, 0
	s_cmp_gt_u32 s48, 29
	s_cbranch_scc0 .LBB0_993
	s_and_b64 vcc, exec, s[12:13]
	s_cbranch_vccz .LBB0_996
	s_barrier

; #define PG8_STAGE(bufoff, gbase, voff) do { _Pragma("unroll") for (int _i = 0; _i < 2; ++_i) \
;         __builtin_amdgcn_global_load_lds((const unsigned*)((const char*)(gbase) + (voff)[_i]), (PG8_LAS unsigned*)(lds + (bufoff) + ldsw + _i * 8192), 16, 0, 0); } while (0)
; #define PG8_LDA(dst, b, h) do { _Pragma("unroll") for (int m = 0; m < 4; ++m) _Pragma("unroll") for (int k = 0; k < 2; ++k) dst[m][k] = *(const PG8_LAS bf16x8*)(lds + PG8_SA(b, h) + aoff + m * 2048 + k * 1024); } while (0)
; #define PG8_MMA(ai, bj, At, Bt) do { __builtin_amdgcn_s_setprio(1); _Pragma("unroll") for (int m = 0; m < 4; ++m) _Pragma("unroll") for (int n = 0; n < 2; ++n) _Pragma("unroll") for (int k = 0; k < 2; ++k) \
;         acc[ai][bj][m][n] = __builtin_amdgcn_mfma_f32_16x16x32_bf16(Bt[n][k], At[m][k], acc[ai][bj][m][n], 0, 0, 0); __builtin_amdgcn_s_setprio(0); } while (0)
; #define PG8_WAIT_V(n) asm volatile("s_waitcnt vmcnt(" #n ")" ::: "memory")
; #define PG8_WAIT_L(n) asm volatile("s_waitcnt lgkmcnt(" #n ")" ::: "memory")
; #define PG8_BAR __builtin_amdgcn_s_barrier()
; #define PG8_SCHED __builtin_amdgcn_sched_barrier(0)
; template <class Epi, class Sched, bool ALIGN_EPI = false, bool SP2 = false>
; __device__ __forceinline__ void gemm_phase(PG8_LAS unsigned char* lds, const Gemm g, const Sched& S, const Epi& E) {
;     ...
;             PG8_WAIT_V(8); PG8_WAIT_L(0); PG8_BAR; PG8_MMA(0, 0, At, B0); PG8_MMA(0, 1, At, B1); PG8_BAR; PG8_SCHED;
;             PG8_LDA(At, 1, 1); PG8_STAGE(PG8_SB(1, 0), b3, voffB); PG8_STAGE(PG8_SB(1, 1), b3 + hstep, voffB); PG8_STAGE(PG8_SA(1, 0), a3, voffA);
;             PG8_WAIT_V(8); PG8_WAIT_L(0); PG8_BAR; PG8_MMA(1, 0, At, B0); PG8_MMA(1, 1, At, B1); PG8_BAR; PG8_SCHED;
;     ...
;         if constexpr (ALIGN_EPI) { if (wr == 0) PG8_BAR; }
.Lgr_p7_2:
	s_waitcnt lgkmcnt(0)
	s_barrier
	s_setprio 1
	v_mfma_f32_16x16x32_bf16 v[116:119], v[166:169], v[198:201], v[116:119]
	v_mfma_f32_16x16x32_bf16 v[112:115], v[174:177], v[198:201], v[112:115]
	v_mfma_f32_16x16x32_bf16 v[108:111], v[166:169], v[206:209], v[108:111]
	v_mfma_f32_16x16x32_bf16 v[100:103], v[174:177], v[206:209], v[100:103]
	v_mfma_f32_16x16x32_bf16 v[92:95], v[166:169], v[214:217], v[92:95]
	v_mfma_f32_16x16x32_bf16 v[84:87], v[174:177], v[214:217], v[84:87]
	v_mfma_f32_16x16x32_bf16 v[76:79], v[166:169], v[226:229], v[76:79]
	v_mfma_f32_16x16x32_bf16 v[68:71], v[174:177], v[226:229], v[68:71]
	v_mfma_f32_16x16x32_bf16 v[116:119], v[170:173], v[202:205], v[116:119]
	v_mfma_f32_16x16x32_bf16 v[112:115], v[178:181], v[202:205], v[112:115]
	v_mfma_f32_16x16x32_bf16 v[108:111], v[170:173], v[210:213], v[108:111]
	v_mfma_f32_16x16x32_bf16 v[100:103], v[178:181], v[210:213], v[100:103]
	v_mfma_f32_16x16x32_bf16 v[92:95], v[170:173], v[222:225], v[92:95]
	v_mfma_f32_16x16x32_bf16 v[84:87], v[178:181], v[222:225], v[84:87]
	v_mfma_f32_16x16x32_bf16 v[76:79], v[170:173], v[230:233], v[76:79]
	v_mfma_f32_16x16x32_bf16 v[68:71], v[178:181], v[230:233], v[68:71]
	s_setprio 0
	s_setprio 1
	v_mfma_f32_16x16x32_bf16 v[124:127], v[182:185], v[198:201], v[124:127]
	v_mfma_f32_16x16x32_bf16 v[120:123], v[190:193], v[198:201], v[120:123]
	v_mfma_f32_16x16x32_bf16 v[104:107], v[182:185], v[206:209], v[104:107]
	v_mfma_f32_16x16x32_bf16 v[96:99], v[190:193], v[206:209], v[96:99]
	v_mfma_f32_16x16x32_bf16 v[88:91], v[182:185], v[214:217], v[88:91]
	v_mfma_f32_16x16x32_bf16 v[80:83], v[190:193], v[214:217], v[80:83]
	v_mfma_f32_16x16x32_bf16 v[72:75], v[182:185], v[226:229], v[72:75]
	v_mfma_f32_16x16x32_bf16 v[64:67], v[190:193], v[226:229], v[64:67]
	v_mfma_f32_16x16x32_bf16 v[124:127], v[186:189], v[202:205], v[124:127]
	v_mfma_f32_16x16x32_bf16 v[120:123], v[194:197], v[202:205], v[120:123]
	v_mfma_f32_16x16x32_bf16 v[104:107], v[186:189], v[210:213], v[104:107]
	v_mfma_f32_16x16x32_bf16 v[96:99], v[194:197], v[210:213], v[96:99]
	v_mfma_f32_16x16x32_bf16 v[88:91], v[186:189], v[222:225], v[88:91]
	v_mfma_f32_16x16x32_bf16 v[80:83], v[194:197], v[222:225], v[80:83]
	v_mfma_f32_16x16x32_bf16 v[72:75], v[186:189], v[230:233], v[72:75]
	v_mfma_f32_16x16x32_bf16 v[64:67], v[194:197], v[230:233], v[64:67]
	s_setprio 0
	s_barrier
	s_add_i32 s28, s52, s30
	s_mov_b32 m0, s28
	ds_read_b128 v[198:201], v164 offset:49152
	ds_read_b128 v[202:205], v164 offset:50176
	ds_read_b128 v[206:209], v164 offset:51200
	ds_read_b128 v[210:213], v164 offset:52224
	global_load_lds_dwordx4 v132, vcc
	s_add_i32 m0, s28, 0x2000
	s_add_u32 s26, s26, 0x80080
	s_addc_u32 s27, s27, 0
	s_add_i32 s28, s53, s30
	global_load_lds_dwordx4 v128, vcc
	s_mov_b32 m0, s28
	ds_read_b128 v[230:233], v164 offset:56320
	global_load_lds_dwordx4 v132, s[26:27]
	s_add_i32 m0, s28, 0x2000
	ds_read_b128 v[226:229], v164 offset:55296
	global_load_lds_dwordx4 v128, s[26:27]
	s_mov_b32 m0, s39
	ds_read_b128 v[222:225], v164 offset:54272
	global_load_lds_dwordx4 v134, s[98:99]
	s_mov_b32 m0, s40
	ds_read_b128 v[214:217], v164 offset:53248
	global_load_lds_dwordx4 v130, s[98:99]
	s_waitcnt vmcnt(8) lgkmcnt(0)
	s_barrier
	s_setprio 1
	v_mfma_f32_16x16x32_bf16 v[60:63], v[166:169], v[198:201], v[60:63]
	v_mfma_f32_16x16x32_bf16 v[52:55], v[174:177], v[198:201], v[52:55]
	v_mfma_f32_16x16x32_bf16 v[44:47], v[166:169], v[206:209], v[44:47]
	v_mfma_f32_16x16x32_bf16 v[36:39], v[174:177], v[206:209], v[36:39]
	v_mfma_f32_16x16x32_bf16 v[28:31], v[166:169], v[214:217], v[28:31]
	v_mfma_f32_16x16x32_bf16 v[20:23], v[174:177], v[214:217], v[20:23]
	v_mfma_f32_16x16x32_bf16 v[12:15], v[166:169], v[226:229], v[12:15]
	v_mfma_f32_16x16x32_bf16 v[4:7], v[174:177], v[226:229], v[4:7]
	v_mfma_f32_16x16x32_bf16 v[60:63], v[170:173], v[202:205], v[60:63]
	v_mfma_f32_16x16x32_bf16 v[52:55], v[178:181], v[202:205], v[52:55]
	v_mfma_f32_16x16x32_bf16 v[44:47], v[170:173], v[210:213], v[44:47]
	v_mfma_f32_16x16x32_bf16 v[36:39], v[178:181], v[210:213], v[36:39]
	v_mfma_f32_16x16x32_bf16 v[28:31], v[170:173], v[222:225], v[28:31]
	v_mfma_f32_16x16x32_bf16 v[20:23], v[178:181], v[222:225], v[20:23]
	v_mfma_f32_16x16x32_bf16 v[12:15], v[170:173], v[230:233], v[12:15]
	v_mfma_f32_16x16x32_bf16 v[4:7], v[178:181], v[230:233], v[4:7]
	s_setprio 0
	s_setprio 1
	v_mfma_f32_16x16x32_bf16 v[56:59], v[182:185], v[198:201], v[56:59]
	v_mfma_f32_16x16x32_bf16 v[48:51], v[190:193], v[198:201], v[48:51]
	v_mfma_f32_16x16x32_bf16 v[40:43], v[182:185], v[206:209], v[40:43]
	v_mfma_f32_16x16x32_bf16 v[32:35], v[190:193], v[206:209], v[32:35]
	v_mfma_f32_16x16x32_bf16 v[24:27], v[182:185], v[214:217], v[24:27]
	v_mfma_f32_16x16x32_bf16 v[16:19], v[190:193], v[214:217], v[16:19]
	v_mfma_f32_16x16x32_bf16 v[8:11], v[182:185], v[226:229], v[8:11]
	v_mfma_f32_16x16x32_bf16 v[0:3], v[190:193], v[226:229], v[0:3]
	v_mfma_f32_16x16x32_bf16 v[56:59], v[186:189], v[202:205], v[56:59]
	v_mfma_f32_16x16x32_bf16 v[48:51], v[194:197], v[202:205], v[48:51]
	v_mfma_f32_16x16x32_bf16 v[40:43], v[186:189], v[210:213], v[40:43]
	v_mfma_f32_16x16x32_bf16 v[32:35], v[194:197], v[210:213], v[32:35]
	v_mfma_f32_16x16x32_bf16 v[24:27], v[186:189], v[222:225], v[24:27]
	v_mfma_f32_16x16x32_bf16 v[16:19], v[194:197], v[222:225], v[16:19]
	v_mfma_f32_16x16x32_bf16 v[8:11], v[186:189], v[230:233], v[8:11]
	v_mfma_f32_16x16x32_bf16 v[0:3], v[194:197], v[230:233], v[0:3]
	s_setprio 0
	s_barrier
	s_mov_b32 s100, 0
	s_add_i32 s51, s51, 2
	s_add_u32 s24, s24, 0x100
	s_addc_u32 s25, s25, 0
	s_add_u32 s49, s49, 0x100
	s_addc_u32 s50, s50, 0
	s_cmp_gt_u32 s51, 29
	s_cbranch_scc0 .LBB0_1076
	s_and_b64 vcc, exec, s[14:15]
	s_cbranch_vccz .LBB0_1079
	s_barrier

; #define PG8_STAGE(bufoff, gbase, voff) do { _Pragma("unroll") for (int _i = 0; _i < 2; ++_i) \
;         __builtin_amdgcn_global_load_lds((const unsigned*)((const char*)(gbase) + (voff)[_i]), (PG8_LAS unsigned*)(lds + (bufoff) + ldsw + _i * 8192), 16, 0, 0); } while (0)
; #define PG8_LDA(dst, b, h) do { _Pragma("unroll") for (int m = 0; m < 4; ++m) _Pragma("unroll") for (int k = 0; k < 2; ++k) dst[m][k] = *(const PG8_LAS bf16x8*)(lds + PG8_SA(b, h) + aoff + m * 2048 + k * 1024); } while (0)
; #define PG8_LDB(dst, b, h) do { _Pragma("unroll") for (int n = 0; n < 2; ++n) _Pragma("unroll") for (int k = 0; k < 2; ++k) dst[n][k] = *(const PG8_LAS bf16x8*)(lds + PG8_SB(b, h) + boff + n * 2048 + k * 1024); } while (0)
; #define PG8_MMA(ai, bj, At, Bt) do { __builtin_amdgcn_s_setprio(1); _Pragma("unroll") for (int m = 0; m < 4; ++m) _Pragma("unroll") for (int n = 0; n < 2; ++n) _Pragma("unroll") for (int k = 0; k < 2; ++k) \
;         acc[ai][bj][m][n] = __builtin_amdgcn_mfma_f32_16x16x32_bf16(Bt[n][k], At[m][k], acc[ai][bj][m][n], 0, 0, 0); __builtin_amdgcn_s_setprio(0); } while (0)
; #define PG8_WAIT_V(n) asm volatile("s_waitcnt vmcnt(" #n ")" ::: "memory")
; #define PG8_WAIT_L(n) asm volatile("s_waitcnt lgkmcnt(" #n ")" ::: "memory")
; template <class Epi, class Sched, bool ALIGN_EPI = false, bool SP2 = false>
; __device__ __forceinline__ void gemm_phase(PG8_LAS unsigned char* lds, const Gemm g, const Sched& S, const Epi& E) {
;     ...
;             const bool last = (t == nt - 2);
;             const char* a1 = cA + (size_t)(t + 1) * kstep;
;             const char* a2 = last ? nA : cA + (size_t)(t + 2) * kstep; const char* b2 = last ? nB : cB + (size_t)(t + 2) * kstep;
;             const char* a3 = a2 + kstep; const char* b3 = b2 + kstep;
;             if (last && has_next) S.a_ready(nxt);
;             if constexpr (SP2) {
;             PG8_LDB(B0, 0, 0); PG8_LDB(B1, 0, 1); PG8_SCHED; PG8_LDA(At, 0, 0); PG8_STAGE(PG8_SA(1, 1), a1 + hstep, voffA);
;             PG8_WAIT_V(8); PG8_WAIT_L(0); PG8_BAR; PG8_MMA(0, 0, At, B0); PG8_MMA(0, 1, At, B1); PG8_BAR; PG8_SCHED;
;             PG8_LDA(At, 0, 1); PG8_STAGE(PG8_SB(0, 0), b2, voffB); PG8_STAGE(PG8_SB(0, 1), b2 + hstep, voffB); PG8_STAGE(PG8_SA(0, 0), a2, voffA);
;             PG8_WAIT_V(8); PG8_WAIT_L(0); PG8_BAR; PG8_MMA(1, 0, At, B0); PG8_MMA(1, 1, At, B1); PG8_BAR; PG8_SCHED;
.LBB0_1107:
	ds_read_b128 v[156:159], v148
	ds_read_b128 v[160:163], v148 offset:1024
	ds_read_b128 v[164:167], v148 offset:2048
	ds_read_b128 v[168:171], v148 offset:3072
	ds_read_b128 v[172:175], v149
	ds_read_b128 v[176:179], v149 offset:1024
	ds_read_b128 v[180:183], v149 offset:2048
	ds_read_b128 v[184:187], v149 offset:3072
	s_add_i32 s56, s30, 2
	s_add_u32 s57, s28, 0x80
	s_addc_u32 s31, s29, 0
	s_cmp_eq_u32 s43, s30
	s_cselect_b32 s30, s4, s57
	s_cselect_b32 s31, s5, s31
	s_cselect_b32 s59, s27, s55
	s_cselect_b32 s58, s26, s54
	v_lshl_add_u64 v[146:147], s[28:29], 0, v[138:139]
	s_add_i32 m0, s36, 0xc000
	ds_read_b128 v[188:191], v150
	ds_read_b128 v[192:195], v150 offset:1024
	ds_read_b128 v[196:199], v150 offset:2048
	ds_read_b128 v[200:203], v150 offset:3072
	ds_read_b128 v[204:207], v150 offset:4096
	ds_read_b128 v[208:211], v150 offset:5120
	ds_read_b128 v[212:215], v150 offset:6144
	ds_read_b128 v[216:219], v150 offset:7168
	global_load_lds_dwordx4 v[146:147], off
	v_lshl_add_u64 v[146:147], s[28:29], 0, v[140:141]
	s_add_i32 m0, s36, 0xe000
	s_nop 0
	global_load_lds_dwordx4 v[146:147], off
	s_waitcnt vmcnt(8) lgkmcnt(0)
	s_barrier
	s_setprio 1
	v_mfma_f32_16x16x32_bf16 v[124:127], v[156:159], v[188:191], v[124:127]
	v_mfma_f32_16x16x32_bf16 v[120:123], v[164:167], v[188:191], v[120:123]
	v_mfma_f32_16x16x32_bf16 v[108:111], v[156:159], v[196:199], v[108:111]
	v_mfma_f32_16x16x32_bf16 v[104:107], v[164:167], v[196:199], v[104:107]
	v_mfma_f32_16x16x32_bf16 v[92:95], v[156:159], v[204:207], v[92:95]
	v_mfma_f32_16x16x32_bf16 v[88:91], v[164:167], v[204:207], v[88:91]
	v_mfma_f32_16x16x32_bf16 v[76:79], v[156:159], v[212:215], v[76:79]
	v_mfma_f32_16x16x32_bf16 v[72:75], v[164:167], v[212:215], v[72:75]
	v_mfma_f32_16x16x32_bf16 v[124:127], v[160:163], v[192:195], v[124:127]
	v_mfma_f32_16x16x32_bf16 v[120:123], v[168:171], v[192:195], v[120:123]
	v_mfma_f32_16x16x32_bf16 v[108:111], v[160:163], v[200:203], v[108:111]
	v_mfma_f32_16x16x32_bf16 v[104:107], v[168:171], v[200:203], v[104:107]
	v_mfma_f32_16x16x32_bf16 v[92:95], v[160:163], v[208:211], v[92:95]
	v_mfma_f32_16x16x32_bf16 v[88:91], v[168:171], v[208:211], v[88:91]
	v_mfma_f32_16x16x32_bf16 v[76:79], v[160:163], v[216:219], v[76:79]
	v_mfma_f32_16x16x32_bf16 v[72:75], v[168:171], v[216:219], v[72:75]
	s_setprio 0
	s_setprio 1
	v_mfma_f32_16x16x32_bf16 v[116:119], v[172:175], v[188:191], v[116:119]
	v_mfma_f32_16x16x32_bf16 v[112:115], v[180:183], v[188:191], v[112:115]
	v_mfma_f32_16x16x32_bf16 v[100:103], v[172:175], v[196:199], v[100:103]
	v_mfma_f32_16x16x32_bf16 v[96:99], v[180:183], v[196:199], v[96:99]
	v_mfma_f32_16x16x32_bf16 v[84:87], v[172:175], v[204:207], v[84:87]
	v_mfma_f32_16x16x32_bf16 v[80:83], v[180:183], v[204:207], v[80:83]
	v_mfma_f32_16x16x32_bf16 v[68:71], v[172:175], v[212:215], v[68:71]
	v_mfma_f32_16x16x32_bf16 v[64:67], v[180:183], v[212:215], v[64:67]
	v_mfma_f32_16x16x32_bf16 v[116:119], v[176:179], v[192:195], v[116:119]
	v_mfma_f32_16x16x32_bf16 v[112:115], v[184:187], v[192:195], v[112:115]
	v_mfma_f32_16x16x32_bf16 v[100:103], v[176:179], v[200:203], v[100:103]
	v_mfma_f32_16x16x32_bf16 v[96:99], v[184:187], v[200:203], v[96:99]
	v_mfma_f32_16x16x32_bf16 v[84:87], v[176:179], v[208:211], v[84:87]
	v_mfma_f32_16x16x32_bf16 v[80:83], v[184:187], v[208:211], v[80:83]
	v_mfma_f32_16x16x32_bf16 v[68:71], v[176:179], v[216:219], v[68:71]
	v_mfma_f32_16x16x32_bf16 v[64:67], v[184:187], v[216:219], v[64:67]
	s_setprio 0
	s_barrier
	s_add_i32 s57, s47, s33
	v_lshl_add_u64 v[146:147], s[58:59], 0, v[130:131]
	s_mov_b32 m0, s57
	ds_read_b128 v[188:191], v150 offset:16384
	ds_read_b128 v[192:195], v150 offset:17408
	ds_read_b128 v[196:199], v150 offset:18432
	ds_read_b128 v[200:203], v150 offset:19456
	ds_read_b128 v[204:207], v150 offset:20480
	ds_read_b128 v[208:211], v150 offset:21504
	ds_read_b128 v[212:215], v150 offset:22528
	ds_read_b128 v[216:219], v150 offset:23552
	global_load_lds_dwordx4 v[146:147], off
	s_add_i32 m0, s57, 0x2000
	v_lshl_add_u64 v[222:223], s[58:59], 0, v[134:135]
	s_add_u32 s58, s58, s10
	s_addc_u32 s59, s59, s11
	s_add_i32 s57, s48, s33
	global_load_lds_dwordx4 v[222:223], off
	v_lshl_add_u64 v[224:225], s[58:59], 0, v[130:131]
	s_mov_b32 m0, s57
	v_lshl_add_u64 v[226:227], s[58:59], 0, v[134:135]
	global_load_lds_dwordx4 v[224:225], off
	s_add_i32 m0, s57, 0x2000
	v_lshl_add_u64 v[228:229], s[30:31], 0, v[128:129]
	global_load_lds_dwordx4 v[226:227], off
	s_mov_b32 m0, s36
	v_lshl_add_u64 v[230:231], s[30:31], 0, v[132:133]
	global_load_lds_dwordx4 v[228:229], off
	s_mov_b32 m0, s37
	s_nop 0
	global_load_lds_dwordx4 v[230:231], off
	s_waitcnt vmcnt(8) lgkmcnt(0)
	s_barrier
; #define PG8_STAGE(bufoff, gbase, voff) do { _Pragma("unroll") for (int _i = 0; _i < 2; ++_i) \
;         __builtin_amdgcn_global_load_lds((const unsigned*)((const char*)(gbase) + (voff)[_i]), (PG8_LAS unsigned*)(lds + (bufoff) + ldsw + _i * 8192), 16, 0, 0); } while (0)
; #define PG8_LDA(dst, b, h) do { _Pragma("unroll") for (int m = 0; m < 4; ++m) _Pragma("unroll") for (int k = 0; k < 2; ++k) dst[m][k] = *(const PG8_LAS bf16x8*)(lds + PG8_SA(b, h) + aoff + m * 2048 + k * 1024); } while (0)
; #define PG8_LDB(dst, b, h) do { _Pragma("unroll") for (int n = 0; n < 2; ++n) _Pragma("unroll") for (int k = 0; k < 2; ++k) dst[n][k] = *(const PG8_LAS bf16x8*)(lds + PG8_SB(b, h) + boff + n * 2048 + k * 1024); } while (0)
; #define PG8_MMA(ai, bj, At, Bt) do { __builtin_amdgcn_s_setprio(1); _Pragma("unroll") for (int m = 0; m < 4; ++m) _Pragma("unroll") for (int n = 0; n < 2; ++n) _Pragma("unroll") for (int k = 0; k < 2; ++k) \
;         acc[ai][bj][m][n] = __builtin_amdgcn_mfma_f32_16x16x32_bf16(Bt[n][k], At[m][k], acc[ai][bj][m][n], 0, 0, 0); __builtin_amdgcn_s_setprio(0); } while (0)
; #define PG8_WAIT_V(n) asm volatile("s_waitcnt vmcnt(" #n ")" ::: "memory")
; #define PG8_WAIT_L(n) asm volatile("s_waitcnt lgkmcnt(" #n ")" ::: "memory")
; #define PG8_BAR __builtin_amdgcn_s_barrier()
; #define PG8_SCHED __builtin_amdgcn_sched_barrier(0)
; template <class Epi, class Sched, bool ALIGN_EPI = false, bool SP2 = false>
; __device__ __forceinline__ void gemm_phase(PG8_LAS unsigned char* lds, const Gemm g, const Sched& S, const Epi& E) {
;     ...
;             PG8_WAIT_V(8); PG8_WAIT_L(0); PG8_BAR; PG8_MMA(1, 0, At, B0); PG8_MMA(1, 1, At, B1); PG8_BAR; PG8_SCHED;
;             PG8_LDB(B0, 1, 0); PG8_LDB(B1, 1, 1); PG8_SCHED; PG8_LDA(At, 1, 0); PG8_STAGE(PG8_SA(0, 1), a2 + hstep, voffA);
;             PG8_WAIT_V(8); PG8_WAIT_L(0); PG8_BAR; PG8_MMA(0, 0, At, B0); PG8_MMA(0, 1, At, B1); PG8_BAR; PG8_SCHED;
	s_setprio 1
	v_mfma_f32_16x16x32_bf16 v[60:63], v[156:159], v[188:191], v[60:63]
	v_mfma_f32_16x16x32_bf16 v[56:59], v[164:167], v[188:191], v[56:59]
	v_mfma_f32_16x16x32_bf16 v[44:47], v[156:159], v[196:199], v[44:47]
	v_mfma_f32_16x16x32_bf16 v[40:43], v[164:167], v[196:199], v[40:43]
	v_mfma_f32_16x16x32_bf16 v[28:31], v[156:159], v[204:207], v[28:31]
	v_mfma_f32_16x16x32_bf16 v[24:27], v[164:167], v[204:207], v[24:27]
	v_mfma_f32_16x16x32_bf16 v[12:15], v[156:159], v[212:215], v[12:15]
	v_mfma_f32_16x16x32_bf16 v[8:11], v[164:167], v[212:215], v[8:11]
	v_mfma_f32_16x16x32_bf16 v[60:63], v[160:163], v[192:195], v[60:63]
	v_mfma_f32_16x16x32_bf16 v[56:59], v[168:171], v[192:195], v[56:59]
	v_mfma_f32_16x16x32_bf16 v[44:47], v[160:163], v[200:203], v[44:47]
	v_mfma_f32_16x16x32_bf16 v[40:43], v[168:171], v[200:203], v[40:43]
	v_mfma_f32_16x16x32_bf16 v[28:31], v[160:163], v[208:211], v[28:31]
	v_mfma_f32_16x16x32_bf16 v[24:27], v[168:171], v[208:211], v[24:27]
	v_mfma_f32_16x16x32_bf16 v[12:15], v[160:163], v[216:219], v[12:15]
	v_mfma_f32_16x16x32_bf16 v[8:11], v[168:171], v[216:219], v[8:11]
	s_setprio 0
	s_setprio 1
	v_mfma_f32_16x16x32_bf16 v[52:55], v[172:175], v[188:191], v[52:55]
	v_mfma_f32_16x16x32_bf16 v[48:51], v[180:183], v[188:191], v[48:51]
	v_mfma_f32_16x16x32_bf16 v[36:39], v[172:175], v[196:199], v[36:39]
	v_mfma_f32_16x16x32_bf16 v[32:35], v[180:183], v[196:199], v[32:35]
	v_mfma_f32_16x16x32_bf16 v[20:23], v[172:175], v[204:207], v[20:23]
	v_mfma_f32_16x16x32_bf16 v[16:19], v[180:183], v[204:207], v[16:19]
	v_mfma_f32_16x16x32_bf16 v[4:7], v[172:175], v[212:215], v[4:7]
	v_mfma_f32_16x16x32_bf16 v[0:3], v[180:183], v[212:215], v[0:3]
	v_mfma_f32_16x16x32_bf16 v[52:55], v[176:179], v[192:195], v[52:55]
	v_mfma_f32_16x16x32_bf16 v[48:51], v[184:187], v[192:195], v[48:51]
	v_mfma_f32_16x16x32_bf16 v[36:39], v[176:179], v[200:203], v[36:39]
	v_mfma_f32_16x16x32_bf16 v[32:35], v[184:187], v[200:203], v[32:35]
	v_mfma_f32_16x16x32_bf16 v[20:23], v[176:179], v[208:211], v[20:23]
	v_mfma_f32_16x16x32_bf16 v[16:19], v[184:187], v[208:211], v[16:19]
	v_mfma_f32_16x16x32_bf16 v[4:7], v[176:179], v[216:219], v[4:7]
	v_mfma_f32_16x16x32_bf16 v[0:3], v[184:187], v[216:219], v[0:3]
	s_setprio 0
	s_barrier
	s_add_i32 s57, 0, 0x18000
	v_add_u32_e32 v153, s57, v151
	s_add_i32 s58, 0, 0x1c000
	ds_read_b128 v[156:159], v153
	ds_read_b128 v[160:163], v153 offset:1024
	ds_read_b128 v[164:167], v153 offset:2048
	ds_read_b128 v[168:171], v153 offset:3072
	v_add_u32_e32 v153, s58, v151
	ds_read_b128 v[172:175], v153
	ds_read_b128 v[176:179], v153 offset:1024
	ds_read_b128 v[180:183], v153 offset:2048
	ds_read_b128 v[184:187], v153 offset:3072
	s_add_u32 s30, s30, s10
	s_addc_u32 s31, s31, s11
	s_mov_b32 m0, s38
	v_lshl_add_u64 v[232:233], s[30:31], 0, v[128:129]
	ds_read_b128 v[188:191], v150 offset:32768
	ds_read_b128 v[192:195], v150 offset:33792
	ds_read_b128 v[196:199], v150 offset:34816
	ds_read_b128 v[200:203], v150 offset:35840
	ds_read_b128 v[204:207], v150 offset:36864
	ds_read_b128 v[208:211], v150 offset:37888
	ds_read_b128 v[212:215], v150 offset:38912
	ds_read_b128 v[216:219], v150 offset:39936
	global_load_lds_dwordx4 v[232:233], off
	v_lshl_add_u64 v[232:233], s[30:31], 0, v[132:133]
	s_mov_b32 m0, s39
	s_nop 0
	global_load_lds_dwordx4 v[232:233], off
	s_waitcnt vmcnt(8) lgkmcnt(0)
	s_barrier
	s_setprio 1
	v_mfma_f32_16x16x32_bf16 v[124:127], v[156:159], v[188:191], v[124:127]
	v_mfma_f32_16x16x32_bf16 v[120:123], v[164:167], v[188:191], v[120:123]
	v_mfma_f32_16x16x32_bf16 v[108:111], v[156:159], v[196:199], v[108:111]
	v_mfma_f32_16x16x32_bf16 v[104:107], v[164:167], v[196:199], v[104:107]
	v_mfma_f32_16x16x32_bf16 v[92:95], v[156:159], v[204:207], v[92:95]
	v_mfma_f32_16x16x32_bf16 v[88:91], v[164:167], v[204:207], v[88:91]
	v_mfma_f32_16x16x32_bf16 v[76:79], v[156:159], v[212:215], v[76:79]
	v_mfma_f32_16x16x32_bf16 v[72:75], v[164:167], v[212:215], v[72:75]
	v_mfma_f32_16x16x32_bf16 v[124:127], v[160:163], v[192:195], v[124:127]
	v_mfma_f32_16x16x32_bf16 v[120:123], v[168:171], v[192:195], v[120:123]
	v_mfma_f32_16x16x32_bf16 v[108:111], v[160:163], v[200:203], v[108:111]
	v_mfma_f32_16x16x32_bf16 v[104:107], v[168:171], v[200:203], v[104:107]
	v_mfma_f32_16x16x32_bf16 v[92:95], v[160:163], v[208:211], v[92:95]
	v_mfma_f32_16x16x32_bf16 v[88:91], v[168:171], v[208:211], v[88:91]
	v_mfma_f32_16x16x32_bf16 v[76:79], v[160:163], v[216:219], v[76:79]
	v_mfma_f32_16x16x32_bf16 v[72:75], v[168:171], v[216:219], v[72:75]
	s_setprio 0
	s_setprio 1
	v_mfma_f32_16x16x32_bf16 v[116:119], v[172:175], v[188:191], v[116:119]
	v_mfma_f32_16x16x32_bf16 v[112:115], v[180:183], v[188:191], v[112:115]
	v_mfma_f32_16x16x32_bf16 v[100:103], v[172:175], v[196:199], v[100:103]
	v_mfma_f32_16x16x32_bf16 v[96:99], v[180:183], v[196:199], v[96:99]
	v_mfma_f32_16x16x32_bf16 v[84:87], v[172:175], v[204:207], v[84:87]
	v_mfma_f32_16x16x32_bf16 v[80:83], v[180:183], v[204:207], v[80:83]
	v_mfma_f32_16x16x32_bf16 v[68:71], v[172:175], v[212:215], v[68:71]
	v_mfma_f32_16x16x32_bf16 v[64:67], v[180:183], v[212:215], v[64:67]
	v_mfma_f32_16x16x32_bf16 v[116:119], v[176:179], v[192:195], v[116:119]
	v_mfma_f32_16x16x32_bf16 v[112:115], v[184:187], v[192:195], v[112:115]
	v_mfma_f32_16x16x32_bf16 v[100:103], v[176:179], v[200:203], v[100:103]
	v_mfma_f32_16x16x32_bf16 v[96:99], v[184:187], v[200:203], v[96:99]
	v_mfma_f32_16x16x32_bf16 v[84:87], v[176:179], v[208:211], v[84:87]
	v_mfma_f32_16x16x32_bf16 v[80:83], v[184:187], v[208:211], v[80:83]
	v_mfma_f32_16x16x32_bf16 v[68:71], v[176:179], v[216:219], v[68:71]
	v_mfma_f32_16x16x32_bf16 v[64:67], v[184:187], v[216:219], v[64:67]
	s_setprio 0
	s_barrier
; #define PG8_STAGE(bufoff, gbase, voff) do { _Pragma("unroll") for (int _i = 0; _i < 2; ++_i) \
;         __builtin_amdgcn_global_load_lds((const unsigned*)((const char*)(gbase) + (voff)[_i]), (PG8_LAS unsigned*)(lds + (bufoff) + ldsw + _i * 8192), 16, 0, 0); } while (0)
; #define PG8_LDA(dst, b, h) do { _Pragma("unroll") for (int m = 0; m < 4; ++m) _Pragma("unroll") for (int k = 0; k < 2; ++k) dst[m][k] = *(const PG8_LAS bf16x8*)(lds + PG8_SA(b, h) + aoff + m * 2048 + k * 1024); } while (0)
; #define PG8_MMA(ai, bj, At, Bt) do { __builtin_amdgcn_s_setprio(1); _Pragma("unroll") for (int m = 0; m < 4; ++m) _Pragma("unroll") for (int n = 0; n < 2; ++n) _Pragma("unroll") for (int k = 0; k < 2; ++k) \
;         acc[ai][bj][m][n] = __builtin_amdgcn_mfma_f32_16x16x32_bf16(Bt[n][k], At[m][k], acc[ai][bj][m][n], 0, 0, 0); __builtin_amdgcn_s_setprio(0); } while (0)
; #define PG8_WAIT_V(n) asm volatile("s_waitcnt vmcnt(" #n ")" ::: "memory")
; #define PG8_WAIT_L(n) asm volatile("s_waitcnt lgkmcnt(" #n ")" ::: "memory")
; #define PG8_BAR __builtin_amdgcn_s_barrier()
; #define PG8_SCHED __builtin_amdgcn_sched_barrier(0)
; template <class Epi, class Sched, bool ALIGN_EPI = false, bool SP2 = false>
; __device__ __forceinline__ void gemm_phase(PG8_LAS unsigned char* lds, const Gemm g, const Sched& S, const Epi& E) {
;     ...
;             PG8_LDA(At, 1, 1); PG8_STAGE(PG8_SB(1, 0), b3, voffB); PG8_STAGE(PG8_SB(1, 1), b3 + hstep, voffB); PG8_STAGE(PG8_SA(1, 0), a3, voffA);
;             PG8_WAIT_V(8); PG8_WAIT_L(0); PG8_BAR; PG8_MMA(1, 0, At, B0); PG8_MMA(1, 1, At, B1); PG8_BAR; PG8_SCHED;
	s_add_i32 s30, s57, s33
	v_lshl_add_u64 v[146:147], v[146:147], 0, s[20:21]
	s_mov_b32 m0, s30
	ds_read_b128 v[188:191], v150 offset:49152
	ds_read_b128 v[192:195], v150 offset:50176
	ds_read_b128 v[196:199], v150 offset:51200
	ds_read_b128 v[200:203], v150 offset:52224
	ds_read_b128 v[204:207], v150 offset:53248
	ds_read_b128 v[208:211], v150 offset:54272
	ds_read_b128 v[212:215], v150 offset:55296
	ds_read_b128 v[216:219], v150 offset:56320
	global_load_lds_dwordx4 v[146:147], off
	v_lshl_add_u64 v[146:147], v[222:223], 0, s[20:21]
	s_add_i32 m0, s30, 0x2000
	s_add_i32 s30, s58, s33
	global_load_lds_dwordx4 v[146:147], off
	v_lshl_add_u64 v[146:147], v[224:225], 0, s[20:21]
	s_mov_b32 m0, s30
	s_nop 0
	global_load_lds_dwordx4 v[146:147], off
	v_lshl_add_u64 v[146:147], v[226:227], 0, s[20:21]
	s_add_i32 m0, s30, 0x2000
	s_nop 0
	global_load_lds_dwordx4 v[146:147], off
	v_lshl_add_u64 v[146:147], v[228:229], 0, s[20:21]
	s_mov_b32 m0, s40
	s_nop 0
	global_load_lds_dwordx4 v[146:147], off
	v_lshl_add_u64 v[146:147], v[230:231], 0, s[20:21]
	s_mov_b32 m0, s41
	s_nop 0
	global_load_lds_dwordx4 v[146:147], off
	s_waitcnt vmcnt(8) lgkmcnt(0)
	s_barrier
	s_setprio 1
	v_mfma_f32_16x16x32_bf16 v[60:63], v[156:159], v[188:191], v[60:63]
	v_mfma_f32_16x16x32_bf16 v[56:59], v[164:167], v[188:191], v[56:59]
	v_mfma_f32_16x16x32_bf16 v[44:47], v[156:159], v[196:199], v[44:47]
	v_mfma_f32_16x16x32_bf16 v[40:43], v[164:167], v[196:199], v[40:43]
	v_mfma_f32_16x16x32_bf16 v[28:31], v[156:159], v[204:207], v[28:31]
	v_mfma_f32_16x16x32_bf16 v[24:27], v[164:167], v[204:207], v[24:27]
	v_mfma_f32_16x16x32_bf16 v[12:15], v[156:159], v[212:215], v[12:15]
	v_mfma_f32_16x16x32_bf16 v[8:11], v[164:167], v[212:215], v[8:11]
	v_mfma_f32_16x16x32_bf16 v[60:63], v[160:163], v[192:195], v[60:63]
	v_mfma_f32_16x16x32_bf16 v[56:59], v[168:171], v[192:195], v[56:59]
	v_mfma_f32_16x16x32_bf16 v[44:47], v[160:163], v[200:203], v[44:47]
	v_mfma_f32_16x16x32_bf16 v[40:43], v[168:171], v[200:203], v[40:43]
	v_mfma_f32_16x16x32_bf16 v[28:31], v[160:163], v[208:211], v[28:31]
	v_mfma_f32_16x16x32_bf16 v[24:27], v[168:171], v[208:211], v[24:27]
	v_mfma_f32_16x16x32_bf16 v[12:15], v[160:163], v[216:219], v[12:15]
	v_mfma_f32_16x16x32_bf16 v[8:11], v[168:171], v[216:219], v[8:11]
	s_setprio 0
	s_setprio 1
	v_mfma_f32_16x16x32_bf16 v[52:55], v[172:175], v[188:191], v[52:55]
	v_mfma_f32_16x16x32_bf16 v[48:51], v[180:183], v[188:191], v[48:51]
	v_mfma_f32_16x16x32_bf16 v[36:39], v[172:175], v[196:199], v[36:39]
	v_mfma_f32_16x16x32_bf16 v[32:35], v[180:183], v[196:199], v[32:35]
	v_mfma_f32_16x16x32_bf16 v[20:23], v[172:175], v[204:207], v[20:23]
	v_mfma_f32_16x16x32_bf16 v[16:19], v[180:183], v[204:207], v[16:19]
	v_mfma_f32_16x16x32_bf16 v[4:7], v[172:175], v[212:215], v[4:7]
	v_mfma_f32_16x16x32_bf16 v[0:3], v[180:183], v[212:215], v[0:3]
	v_mfma_f32_16x16x32_bf16 v[52:55], v[176:179], v[192:195], v[52:55]
	v_mfma_f32_16x16x32_bf16 v[48:51], v[184:187], v[192:195], v[48:51]
	v_mfma_f32_16x16x32_bf16 v[36:39], v[176:179], v[200:203], v[36:39]
	v_mfma_f32_16x16x32_bf16 v[32:35], v[184:187], v[200:203], v[32:35]
	v_mfma_f32_16x16x32_bf16 v[20:23], v[176:179], v[208:211], v[20:23]
	v_mfma_f32_16x16x32_bf16 v[16:19], v[184:187], v[208:211], v[16:19]
	v_mfma_f32_16x16x32_bf16 v[4:7], v[176:179], v[216:219], v[4:7]
	v_mfma_f32_16x16x32_bf16 v[0:3], v[184:187], v[216:219], v[0:3]
	s_setprio 0
	s_barrier
	s_add_u32 s28, s28, 0x100
	s_addc_u32 s29, s29, 0
	s_add_u32 s54, s54, 0x100
	s_addc_u32 s55, s55, 0
	s_cmp_ge_i32 s56, s42
	s_mov_b32 s30, s56
	s_cbranch_scc0 .LBB0_1107

; #define PG8_STAGE(bufoff, gbase, voff) do { _Pragma("unroll") for (int _i = 0; _i < 2; ++_i) \
;         __builtin_amdgcn_global_load_lds((const unsigned*)((const char*)(gbase) + (voff)[_i]), (PG8_LAS unsigned*)(lds + (bufoff) + ldsw + _i * 8192), 16, 0, 0); } while (0)
; #define PG8_LDA(dst, b, h) do { _Pragma("unroll") for (int m = 0; m < 4; ++m) _Pragma("unroll") for (int k = 0; k < 2; ++k) dst[m][k] = *(const PG8_LAS bf16x8*)(lds + PG8_SA(b, h) + aoff + m * 2048 + k * 1024); } while (0)
; #define PG8_LDB(dst, b, h) do { _Pragma("unroll") for (int n = 0; n < 2; ++n) _Pragma("unroll") for (int k = 0; k < 2; ++k) dst[n][k] = *(const PG8_LAS bf16x8*)(lds + PG8_SB(b, h) + boff + n * 2048 + k * 1024); } while (0)
; #define PG8_MMA(ai, bj, At, Bt) do { __builtin_amdgcn_s_setprio(1); _Pragma("unroll") for (int m = 0; m < 4; ++m) _Pragma("unroll") for (int n = 0; n < 2; ++n) _Pragma("unroll") for (int k = 0; k < 2; ++k) \
;         acc[ai][bj][m][n] = __builtin_amdgcn_mfma_f32_16x16x32_bf16(Bt[n][k], At[m][k], acc[ai][bj][m][n], 0, 0, 0); __builtin_amdgcn_s_setprio(0); } while (0)
; #define PG8_WAIT_V(n) asm volatile("s_waitcnt vmcnt(" #n ")" ::: "memory")
; #define PG8_WAIT_L(n) asm volatile("s_waitcnt lgkmcnt(" #n ")" ::: "memory")
; template <class Epi, class Sched, bool ALIGN_EPI = false, bool SP2 = false>
; __device__ __forceinline__ void gemm_phase(PG8_LAS unsigned char* lds, const Gemm g, const Sched& S, const Epi& E) {
;     ...
;             const bool last = (t == nt - 2);
;             const char* a1 = cA + (size_t)(t + 1) * kstep;
;             const char* a2 = last ? nA : cA + (size_t)(t + 2) * kstep; const char* b2 = last ? nB : cB + (size_t)(t + 2) * kstep;
;             const char* a3 = a2 + kstep; const char* b3 = b2 + kstep;
;             if (last && has_next) S.a_ready(nxt);
;             if constexpr (SP2) {
;             PG8_LDB(B0, 0, 0); PG8_LDB(B1, 0, 1); PG8_SCHED; PG8_LDA(At, 0, 0); PG8_STAGE(PG8_SA(1, 1), a1 + hstep, voffA);
;             PG8_WAIT_V(8); PG8_WAIT_L(0); PG8_BAR; PG8_MMA(0, 0, At, B0); PG8_MMA(0, 1, At, B1); PG8_BAR; PG8_SCHED;
;             PG8_LDA(At, 0, 1); PG8_STAGE(PG8_SB(0, 0), b2, voffB); PG8_STAGE(PG8_SB(0, 1), b2 + hstep, voffB); PG8_STAGE(PG8_SA(0, 0), a2, voffA);
;             PG8_WAIT_V(8); PG8_WAIT_L(0); PG8_BAR; PG8_MMA(1, 0, At, B0); PG8_MMA(1, 1, At, B1); PG8_BAR; PG8_SCHED;
.LBB0_1204:
	ds_read_b128 v[128:131], v213
	ds_read_b128 v[132:135], v213 offset:1024
	ds_read_b128 v[136:139], v213 offset:2048
	ds_read_b128 v[140:143], v213 offset:3072
	ds_read_b128 v[144:147], v214
	ds_read_b128 v[148:151], v214 offset:1024
	ds_read_b128 v[152:155], v214 offset:2048
	ds_read_b128 v[156:159], v214 offset:3072
	s_add_u32 s22, s20, 0xffea0080
	s_addc_u32 s23, s21, -1
	s_cmpk_eq_i32 s46, 0x54
	s_cselect_b32 s25, s5, s23
	s_cselect_b32 s24, s4, s22
	s_cselect_b32 s23, s19, s45
	s_cselect_b32 s22, s18, s44
	s_add_i32 m0, s27, 0xc000
	ds_read_b128 v[160:163], v215
	ds_read_b128 v[164:167], v215 offset:1024
	ds_read_b128 v[168:171], v215 offset:2048
	ds_read_b128 v[172:175], v215 offset:3072
	ds_read_b128 v[192:195], v215 offset:4096
	ds_read_b128 v[196:199], v215 offset:5120
	ds_read_b128 v[200:203], v215 offset:6144
	global_load_lds_dwordx4 v184, s[20:21]
	s_add_i32 m0, s27, 0xe000
	ds_read_b128 v[204:207], v215 offset:7168
	global_load_lds_dwordx4 v186, s[20:21]
	s_waitcnt vmcnt(8) lgkmcnt(0)
	s_barrier
	s_setprio 1
	v_mfma_f32_16x16x32_bf16 v[124:127], v[128:131], v[160:163], v[124:127]
	v_mfma_f32_16x16x32_bf16 v[120:123], v[136:139], v[160:163], v[120:123]
	v_mfma_f32_16x16x32_bf16 v[108:111], v[128:131], v[168:171], v[108:111]
	v_mfma_f32_16x16x32_bf16 v[104:107], v[136:139], v[168:171], v[104:107]
	v_mfma_f32_16x16x32_bf16 v[92:95], v[128:131], v[192:195], v[92:95]
	v_mfma_f32_16x16x32_bf16 v[88:91], v[136:139], v[192:195], v[88:91]
	v_mfma_f32_16x16x32_bf16 v[76:79], v[128:131], v[200:203], v[76:79]
	v_mfma_f32_16x16x32_bf16 v[72:75], v[136:139], v[200:203], v[72:75]
	v_mfma_f32_16x16x32_bf16 v[124:127], v[132:135], v[164:167], v[124:127]
	v_mfma_f32_16x16x32_bf16 v[120:123], v[140:143], v[164:167], v[120:123]
	v_mfma_f32_16x16x32_bf16 v[108:111], v[132:135], v[172:175], v[108:111]
	v_mfma_f32_16x16x32_bf16 v[104:107], v[140:143], v[172:175], v[104:107]
	v_mfma_f32_16x16x32_bf16 v[92:95], v[132:135], v[196:199], v[92:95]
	v_mfma_f32_16x16x32_bf16 v[88:91], v[140:143], v[196:199], v[88:91]
	v_mfma_f32_16x16x32_bf16 v[76:79], v[132:135], v[204:207], v[76:79]
	v_mfma_f32_16x16x32_bf16 v[72:75], v[140:143], v[204:207], v[72:75]
	s_setprio 0
	s_setprio 1
	v_mfma_f32_16x16x32_bf16 v[116:119], v[144:147], v[160:163], v[116:119]
	v_mfma_f32_16x16x32_bf16 v[112:115], v[152:155], v[160:163], v[112:115]
	v_mfma_f32_16x16x32_bf16 v[100:103], v[144:147], v[168:171], v[100:103]
	v_mfma_f32_16x16x32_bf16 v[96:99], v[152:155], v[168:171], v[96:99]
	v_mfma_f32_16x16x32_bf16 v[84:87], v[144:147], v[192:195], v[84:87]
	v_mfma_f32_16x16x32_bf16 v[80:83], v[152:155], v[192:195], v[80:83]
	v_mfma_f32_16x16x32_bf16 v[68:71], v[144:147], v[200:203], v[68:71]
	v_mfma_f32_16x16x32_bf16 v[64:67], v[152:155], v[200:203], v[64:67]
	v_mfma_f32_16x16x32_bf16 v[116:119], v[148:151], v[164:167], v[116:119]
	v_mfma_f32_16x16x32_bf16 v[112:115], v[156:159], v[164:167], v[112:115]
	v_mfma_f32_16x16x32_bf16 v[100:103], v[148:151], v[172:175], v[100:103]
	v_mfma_f32_16x16x32_bf16 v[96:99], v[156:159], v[172:175], v[96:99]
	v_mfma_f32_16x16x32_bf16 v[84:87], v[148:151], v[196:199], v[84:87]
	v_mfma_f32_16x16x32_bf16 v[80:83], v[156:159], v[196:199], v[80:83]
	v_mfma_f32_16x16x32_bf16 v[68:71], v[148:151], v[204:207], v[68:71]
	v_mfma_f32_16x16x32_bf16 v[64:67], v[156:159], v[204:207], v[64:67]
	s_setprio 0
	s_barrier
	s_add_i32 s47, s38, s26
	s_add_u32 vcc_lo, s22, 0x80
	s_addc_u32 vcc_hi, s23, 0
	s_mov_b32 m0, s47
	ds_read_b128 v[160:163], v215 offset:16384
	ds_read_b128 v[164:167], v215 offset:17408
	ds_read_b128 v[168:171], v215 offset:18432
	ds_read_b128 v[172:175], v215 offset:19456
	global_load_lds_dwordx4 v178, s[22:23]
	s_add_i32 m0, s47, 0x2000
	s_add_u32 s48, s22, 0x160000
	s_addc_u32 s49, s23, 0
	s_add_i32 s47, s39, s26
	global_load_lds_dwordx4 v182, s[22:23]
	s_mov_b32 m0, s47
	ds_read_b128 v[204:207], v215 offset:23552
	global_load_lds_dwordx4 v178, s[48:49]
	s_add_i32 m0, s47, 0x2000
	ds_read_b128 v[200:203], v215 offset:22528
	global_load_lds_dwordx4 v182, s[48:49]
	s_add_u32 s98, s24, 0x80
	s_addc_u32 s99, s25, 0
	s_mov_b32 m0, s27
	ds_read_b128 v[196:199], v215 offset:21504
	global_load_lds_dwordx4 v176, s[24:25]
	s_mov_b32 m0, s28
	ds_read_b128 v[192:195], v215 offset:20480
	global_load_lds_dwordx4 v180, s[24:25]
	s_waitcnt vmcnt(8) lgkmcnt(0)
	s_barrier
	s_setprio 1
	v_mfma_f32_16x16x32_bf16 v[60:63], v[128:131], v[160:163], v[60:63]
	v_mfma_f32_16x16x32_bf16 v[56:59], v[136:139], v[160:163], v[56:59]
	v_mfma_f32_16x16x32_bf16 v[44:47], v[128:131], v[168:171], v[44:47]
	v_mfma_f32_16x16x32_bf16 v[40:43], v[136:139], v[168:171], v[40:43]
	v_mfma_f32_16x16x32_bf16 v[28:31], v[128:131], v[192:195], v[28:31]
	v_mfma_f32_16x16x32_bf16 v[24:27], v[136:139], v[192:195], v[24:27]
	v_mfma_f32_16x16x32_bf16 v[12:15], v[128:131], v[200:203], v[12:15]
	v_mfma_f32_16x16x32_bf16 v[8:11], v[136:139], v[200:203], v[8:11]
	v_mfma_f32_16x16x32_bf16 v[60:63], v[132:135], v[164:167], v[60:63]
	v_mfma_f32_16x16x32_bf16 v[56:59], v[140:143], v[164:167], v[56:59]
	v_mfma_f32_16x16x32_bf16 v[44:47], v[132:135], v[172:175], v[44:47]
	v_mfma_f32_16x16x32_bf16 v[40:43], v[140:143], v[172:175], v[40:43]
	v_mfma_f32_16x16x32_bf16 v[28:31], v[132:135], v[196:199], v[28:31]
	v_mfma_f32_16x16x32_bf16 v[24:27], v[140:143], v[196:199], v[24:27]
	v_mfma_f32_16x16x32_bf16 v[12:15], v[132:135], v[204:207], v[12:15]
	v_mfma_f32_16x16x32_bf16 v[8:11], v[140:143], v[204:207], v[8:11]
	s_setprio 0
	s_setprio 1
	v_mfma_f32_16x16x32_bf16 v[52:55], v[144:147], v[160:163], v[52:55]
	v_mfma_f32_16x16x32_bf16 v[48:51], v[152:155], v[160:163], v[48:51]
	v_mfma_f32_16x16x32_bf16 v[36:39], v[144:147], v[168:171], v[36:39]
	v_mfma_f32_16x16x32_bf16 v[32:35], v[152:155], v[168:171], v[32:35]
	v_mfma_f32_16x16x32_bf16 v[20:23], v[144:147], v[192:195], v[20:23]
	v_mfma_f32_16x16x32_bf16 v[16:19], v[152:155], v[192:195], v[16:19]
	v_mfma_f32_16x16x32_bf16 v[4:7], v[144:147], v[200:203], v[4:7]
	v_mfma_f32_16x16x32_bf16 v[0:3], v[152:155], v[200:203], v[0:3]
	v_mfma_f32_16x16x32_bf16 v[52:55], v[148:151], v[164:167], v[52:55]
	v_mfma_f32_16x16x32_bf16 v[48:51], v[156:159], v[164:167], v[48:51]
	v_mfma_f32_16x16x32_bf16 v[36:39], v[148:151], v[172:175], v[36:39]
	v_mfma_f32_16x16x32_bf16 v[32:35], v[156:159], v[172:175], v[32:35]
	v_mfma_f32_16x16x32_bf16 v[20:23], v[148:151], v[196:199], v[20:23]
	v_mfma_f32_16x16x32_bf16 v[16:19], v[156:159], v[196:199], v[16:19]
	v_mfma_f32_16x16x32_bf16 v[4:7], v[148:151], v[204:207], v[4:7]
	v_mfma_f32_16x16x32_bf16 v[0:3], v[156:159], v[204:207], v[0:3]
	s_setprio 0
	s_barrier
; #define PG8_STAGE(bufoff, gbase, voff) do { _Pragma("unroll") for (int _i = 0; _i < 2; ++_i) \
;         __builtin_amdgcn_global_load_lds((const unsigned*)((const char*)(gbase) + (voff)[_i]), (PG8_LAS unsigned*)(lds + (bufoff) + ldsw + _i * 8192), 16, 0, 0); } while (0)
; #define PG8_LDA(dst, b, h) do { _Pragma("unroll") for (int m = 0; m < 4; ++m) _Pragma("unroll") for (int k = 0; k < 2; ++k) dst[m][k] = *(const PG8_LAS bf16x8*)(lds + PG8_SA(b, h) + aoff + m * 2048 + k * 1024); } while (0)
; #define PG8_LDB(dst, b, h) do { _Pragma("unroll") for (int n = 0; n < 2; ++n) _Pragma("unroll") for (int k = 0; k < 2; ++k) dst[n][k] = *(const PG8_LAS bf16x8*)(lds + PG8_SB(b, h) + boff + n * 2048 + k * 1024); } while (0)
; #define PG8_MMA(ai, bj, At, Bt) do { __builtin_amdgcn_s_setprio(1); _Pragma("unroll") for (int m = 0; m < 4; ++m) _Pragma("unroll") for (int n = 0; n < 2; ++n) _Pragma("unroll") for (int k = 0; k < 2; ++k) \
;         acc[ai][bj][m][n] = __builtin_amdgcn_mfma_f32_16x16x32_bf16(Bt[n][k], At[m][k], acc[ai][bj][m][n], 0, 0, 0); __builtin_amdgcn_s_setprio(0); } while (0)
; #define PG8_WAIT_V(n) asm volatile("s_waitcnt vmcnt(" #n ")" ::: "memory")
; #define PG8_WAIT_L(n) asm volatile("s_waitcnt lgkmcnt(" #n ")" ::: "memory")
; #define PG8_BAR __builtin_amdgcn_s_barrier()
; #define PG8_SCHED __builtin_amdgcn_sched_barrier(0)
; template <class Epi, class Sched, bool ALIGN_EPI = false, bool SP2 = false>
; __device__ __forceinline__ void gemm_phase(PG8_LAS unsigned char* lds, const Gemm g, const Sched& S, const Epi& E) {
;     ...
;             PG8_LDB(B0, 1, 0); PG8_LDB(B1, 1, 1); PG8_SCHED; PG8_LDA(At, 1, 0); PG8_STAGE(PG8_SA(0, 1), a2 + hstep, voffA);
;             PG8_WAIT_V(8); PG8_WAIT_L(0); PG8_BAR; PG8_MMA(0, 0, At, B0); PG8_MMA(0, 1, At, B1); PG8_BAR; PG8_SCHED;
;             PG8_LDA(At, 1, 1); PG8_STAGE(PG8_SB(1, 0), b3, voffB); PG8_STAGE(PG8_SB(1, 1), b3 + hstep, voffB); PG8_STAGE(PG8_SA(1, 0), a3, voffA);
;             PG8_WAIT_V(8); PG8_WAIT_L(0); PG8_BAR; PG8_MMA(1, 0, At, B0); PG8_MMA(1, 1, At, B1); PG8_BAR; PG8_SCHED;
;     ...
;         if constexpr (ALIGN_EPI) { if (wr == 0) PG8_BAR; }
	s_add_i32 s47, 0, 0x18000
	s_add_i32 s48, 0, 0x1c000
	v_add_u32_e32 v140, s47, v211
	v_add_u32_e32 v156, s48, v211
	ds_read_b128 v[128:131], v140
	ds_read_b128 v[132:135], v140 offset:1024
	ds_read_b128 v[136:139], v140 offset:2048
	ds_read_b128 v[140:143], v140 offset:3072
	ds_read_b128 v[144:147], v156
	ds_read_b128 v[148:151], v156 offset:1024
	ds_read_b128 v[152:155], v156 offset:2048
	ds_read_b128 v[156:159], v156 offset:3072
	s_add_u32 s24, s24, 0x160000
	s_addc_u32 s25, s25, 0
	s_mov_b32 m0, s29
	ds_read_b128 v[160:163], v215 offset:32768
	ds_read_b128 v[164:167], v215 offset:33792
	ds_read_b128 v[168:171], v215 offset:34816
	ds_read_b128 v[172:175], v215 offset:35840
	ds_read_b128 v[192:195], v215 offset:36864
	ds_read_b128 v[196:199], v215 offset:37888
	ds_read_b128 v[200:203], v215 offset:38912
	global_load_lds_dwordx4 v176, s[24:25]
	s_mov_b32 m0, s30
	ds_read_b128 v[204:207], v215 offset:39936
	global_load_lds_dwordx4 v180, s[24:25]
	s_waitcnt vmcnt(8) lgkmcnt(0)
	s_barrier
	s_setprio 1
	v_mfma_f32_16x16x32_bf16 v[124:127], v[128:131], v[160:163], v[124:127]
	v_mfma_f32_16x16x32_bf16 v[120:123], v[136:139], v[160:163], v[120:123]
	v_mfma_f32_16x16x32_bf16 v[108:111], v[128:131], v[168:171], v[108:111]
	v_mfma_f32_16x16x32_bf16 v[104:107], v[136:139], v[168:171], v[104:107]
	v_mfma_f32_16x16x32_bf16 v[92:95], v[128:131], v[192:195], v[92:95]
	v_mfma_f32_16x16x32_bf16 v[88:91], v[136:139], v[192:195], v[88:91]
	v_mfma_f32_16x16x32_bf16 v[76:79], v[128:131], v[200:203], v[76:79]
	v_mfma_f32_16x16x32_bf16 v[72:75], v[136:139], v[200:203], v[72:75]
	v_mfma_f32_16x16x32_bf16 v[124:127], v[132:135], v[164:167], v[124:127]
	v_mfma_f32_16x16x32_bf16 v[120:123], v[140:143], v[164:167], v[120:123]
	v_mfma_f32_16x16x32_bf16 v[108:111], v[132:135], v[172:175], v[108:111]
	v_mfma_f32_16x16x32_bf16 v[104:107], v[140:143], v[172:175], v[104:107]
	v_mfma_f32_16x16x32_bf16 v[92:95], v[132:135], v[196:199], v[92:95]
	v_mfma_f32_16x16x32_bf16 v[88:91], v[140:143], v[196:199], v[88:91]
	v_mfma_f32_16x16x32_bf16 v[76:79], v[132:135], v[204:207], v[76:79]
	v_mfma_f32_16x16x32_bf16 v[72:75], v[140:143], v[204:207], v[72:75]
	s_setprio 0
	s_setprio 1
	v_mfma_f32_16x16x32_bf16 v[116:119], v[144:147], v[160:163], v[116:119]
	v_mfma_f32_16x16x32_bf16 v[112:115], v[152:155], v[160:163], v[112:115]
	v_mfma_f32_16x16x32_bf16 v[100:103], v[144:147], v[168:171], v[100:103]
	v_mfma_f32_16x16x32_bf16 v[96:99], v[152:155], v[168:171], v[96:99]
	v_mfma_f32_16x16x32_bf16 v[84:87], v[144:147], v[192:195], v[84:87]
	v_mfma_f32_16x16x32_bf16 v[80:83], v[152:155], v[192:195], v[80:83]
	v_mfma_f32_16x16x32_bf16 v[68:71], v[144:147], v[200:203], v[68:71]
	v_mfma_f32_16x16x32_bf16 v[64:67], v[152:155], v[200:203], v[64:67]
	v_mfma_f32_16x16x32_bf16 v[116:119], v[148:151], v[164:167], v[116:119]
	v_mfma_f32_16x16x32_bf16 v[112:115], v[156:159], v[164:167], v[112:115]
	v_mfma_f32_16x16x32_bf16 v[100:103], v[148:151], v[172:175], v[100:103]
	v_mfma_f32_16x16x32_bf16 v[96:99], v[156:159], v[172:175], v[96:99]
	v_mfma_f32_16x16x32_bf16 v[84:87], v[148:151], v[196:199], v[84:87]
	v_mfma_f32_16x16x32_bf16 v[80:83], v[156:159], v[196:199], v[80:83]
	v_mfma_f32_16x16x32_bf16 v[68:71], v[148:151], v[204:207], v[68:71]
	v_mfma_f32_16x16x32_bf16 v[64:67], v[156:159], v[204:207], v[64:67]
	s_setprio 0
	s_barrier
	s_add_i32 s24, s47, s26
	s_mov_b32 m0, s24
	ds_read_b128 v[160:163], v215 offset:49152
	ds_read_b128 v[164:167], v215 offset:50176
	ds_read_b128 v[168:171], v215 offset:51200
	ds_read_b128 v[172:175], v215 offset:52224
	global_load_lds_dwordx4 v178, vcc
	s_add_i32 m0, s24, 0x2000
	s_add_u32 s22, s22, 0x160080
	s_addc_u32 s23, s23, 0
	s_add_i32 s24, s48, s26
	global_load_lds_dwordx4 v182, vcc
	s_mov_b32 m0, s24
	ds_read_b128 v[204:207], v215 offset:56320
	global_load_lds_dwordx4 v178, s[22:23]
	s_add_i32 m0, s24, 0x2000
	ds_read_b128 v[200:203], v215 offset:55296
	global_load_lds_dwordx4 v182, s[22:23]
	s_mov_b32 m0, s33
	ds_read_b128 v[196:199], v215 offset:54272
	global_load_lds_dwordx4 v176, s[98:99]
	s_mov_b32 m0, s34
	ds_read_b128 v[192:195], v215 offset:53248
	global_load_lds_dwordx4 v180, s[98:99]
	s_waitcnt vmcnt(8) lgkmcnt(0)
	s_barrier
	s_setprio 1
	v_mfma_f32_16x16x32_bf16 v[60:63], v[128:131], v[160:163], v[60:63]
	v_mfma_f32_16x16x32_bf16 v[56:59], v[136:139], v[160:163], v[56:59]
	v_mfma_f32_16x16x32_bf16 v[44:47], v[128:131], v[168:171], v[44:47]
	v_mfma_f32_16x16x32_bf16 v[40:43], v[136:139], v[168:171], v[40:43]
	v_mfma_f32_16x16x32_bf16 v[28:31], v[128:131], v[192:195], v[28:31]
	v_mfma_f32_16x16x32_bf16 v[24:27], v[136:139], v[192:195], v[24:27]
	v_mfma_f32_16x16x32_bf16 v[12:15], v[128:131], v[200:203], v[12:15]
	v_mfma_f32_16x16x32_bf16 v[8:11], v[136:139], v[200:203], v[8:11]
	v_mfma_f32_16x16x32_bf16 v[60:63], v[132:135], v[164:167], v[60:63]
	v_mfma_f32_16x16x32_bf16 v[56:59], v[140:143], v[164:167], v[56:59]
	v_mfma_f32_16x16x32_bf16 v[44:47], v[132:135], v[172:175], v[44:47]
	v_mfma_f32_16x16x32_bf16 v[40:43], v[140:143], v[172:175], v[40:43]
	v_mfma_f32_16x16x32_bf16 v[28:31], v[132:135], v[196:199], v[28:31]
	v_mfma_f32_16x16x32_bf16 v[24:27], v[140:143], v[196:199], v[24:27]
	v_mfma_f32_16x16x32_bf16 v[12:15], v[132:135], v[204:207], v[12:15]
	v_mfma_f32_16x16x32_bf16 v[8:11], v[140:143], v[204:207], v[8:11]
	s_setprio 0
	s_setprio 1
	v_mfma_f32_16x16x32_bf16 v[52:55], v[144:147], v[160:163], v[52:55]
	v_mfma_f32_16x16x32_bf16 v[48:51], v[152:155], v[160:163], v[48:51]
	v_mfma_f32_16x16x32_bf16 v[36:39], v[144:147], v[168:171], v[36:39]
	v_mfma_f32_16x16x32_bf16 v[32:35], v[152:155], v[168:171], v[32:35]
	v_mfma_f32_16x16x32_bf16 v[20:23], v[144:147], v[192:195], v[20:23]
	v_mfma_f32_16x16x32_bf16 v[16:19], v[152:155], v[192:195], v[16:19]
	v_mfma_f32_16x16x32_bf16 v[4:7], v[144:147], v[200:203], v[4:7]
	v_mfma_f32_16x16x32_bf16 v[0:3], v[152:155], v[200:203], v[0:3]
	v_mfma_f32_16x16x32_bf16 v[52:55], v[148:151], v[164:167], v[52:55]
	v_mfma_f32_16x16x32_bf16 v[48:51], v[156:159], v[164:167], v[48:51]
	v_mfma_f32_16x16x32_bf16 v[36:39], v[148:151], v[172:175], v[36:39]
	v_mfma_f32_16x16x32_bf16 v[32:35], v[156:159], v[172:175], v[32:35]
	v_mfma_f32_16x16x32_bf16 v[20:23], v[148:151], v[196:199], v[20:23]
	v_mfma_f32_16x16x32_bf16 v[16:19], v[156:159], v[196:199], v[16:19]
	v_mfma_f32_16x16x32_bf16 v[4:7], v[148:151], v[204:207], v[4:7]
	v_mfma_f32_16x16x32_bf16 v[0:3], v[156:159], v[204:207], v[0:3]
	s_setprio 0
	s_barrier
	s_add_i32 s46, s46, 2
	s_add_u32 s20, s20, 0x100
	s_addc_u32 s21, s21, 0
	s_add_u32 s44, s44, 0x100
	s_addc_u32 s45, s45, 0
	s_cmpk_gt_u32 s46, 0x55
	s_cbranch_scc0 .LBB0_1204
	s_and_b64 vcc, exec, s[16:17]
	s_cbranch_vccz .LBB0_1207
	s_barrier

; #define PG8_STAGE(bufoff, gbase, voff) do { _Pragma("unroll") for (int _i = 0; _i < 2; ++_i) \
;         __builtin_amdgcn_global_load_lds((const unsigned*)((const char*)(gbase) + (voff)[_i]), (PG8_LAS unsigned*)(lds + (bufoff) + ldsw + _i * 8192), 16, 0, 0); } while (0)
; #define PG8_LDA(dst, b, h) do { _Pragma("unroll") for (int m = 0; m < 4; ++m) _Pragma("unroll") for (int k = 0; k < 2; ++k) dst[m][k] = *(const PG8_LAS bf16x8*)(lds + PG8_SA(b, h) + aoff + m * 2048 + k * 1024); } while (0)
; #define PG8_LDB(dst, b, h) do { _Pragma("unroll") for (int n = 0; n < 2; ++n) _Pragma("unroll") for (int k = 0; k < 2; ++k) dst[n][k] = *(const PG8_LAS bf16x8*)(lds + PG8_SB(b, h) + boff + n * 2048 + k * 1024); } while (0)
; #define PG8_MMA(ai, bj, At, Bt) do { __builtin_amdgcn_s_setprio(1); _Pragma("unroll") for (int m = 0; m < 4; ++m) _Pragma("unroll") for (int n = 0; n < 2; ++n) _Pragma("unroll") for (int k = 0; k < 2; ++k) \
;         acc[ai][bj][m][n] = __builtin_amdgcn_mfma_f32_16x16x32_bf16(Bt[n][k], At[m][k], acc[ai][bj][m][n], 0, 0, 0); __builtin_amdgcn_s_setprio(0); } while (0)
; #define PG8_WAIT_V(n) asm volatile("s_waitcnt vmcnt(" #n ")" ::: "memory")
; #define PG8_WAIT_L(n) asm volatile("s_waitcnt lgkmcnt(" #n ")" ::: "memory")
; template <class Epi, class Sched, bool ALIGN_EPI = false, bool SP2 = false>
; __device__ __forceinline__ void gemm_phase(PG8_LAS unsigned char* lds, const Gemm g, const Sched& S, const Epi& E) {
;     ...
;             const bool last = (t == nt - 2);
;             const char* a1 = cA + (size_t)(t + 1) * kstep;
;             const char* a2 = last ? nA : cA + (size_t)(t + 2) * kstep; const char* b2 = last ? nB : cB + (size_t)(t + 2) * kstep;
;             const char* a3 = a2 + kstep; const char* b3 = b2 + kstep;
;             if (last && has_next) S.a_ready(nxt);
;             if constexpr (SP2) {
;             PG8_LDB(B0, 0, 0); PG8_LDB(B1, 0, 1); PG8_SCHED; PG8_LDA(At, 0, 0); PG8_STAGE(PG8_SA(1, 1), a1 + hstep, voffA);
;             PG8_WAIT_V(8); PG8_WAIT_L(0); PG8_BAR; PG8_MMA(0, 0, At, B0); PG8_MMA(0, 1, At, B1); PG8_BAR; PG8_SCHED;
;             PG8_LDA(At, 0, 1); PG8_STAGE(PG8_SB(0, 0), b2, voffB); PG8_STAGE(PG8_SB(0, 1), b2 + hstep, voffB); PG8_STAGE(PG8_SA(0, 0), a2, voffA);
;             PG8_WAIT_V(8); PG8_WAIT_L(0); PG8_BAR; PG8_MMA(1, 0, At, B0); PG8_MMA(1, 1, At, B1); PG8_BAR; PG8_SCHED;
.LBB0_1295:
	ds_read_b128 v[56:59], v203
	ds_read_b128 v[64:67], v203 offset:1024
	ds_read_b128 v[72:75], v203 offset:2048
	ds_read_b128 v[76:79], v203 offset:3072
	ds_read_b128 v[144:147], v204
	ds_read_b128 v[148:151], v204 offset:1024
	ds_read_b128 v[152:155], v204 offset:2048
	ds_read_b128 v[156:159], v204 offset:3072
	s_add_u32 s36, s34, 0xfff80080
	s_addc_u32 s37, s35, -1
	s_cmp_eq_u32 s56, 28
	s_cselect_b32 s39, s27, s37
	s_cselect_b32 s38, s52, s36
	s_cselect_b32 s37, s25, s55
	s_cselect_b32 s36, s53, s54
	s_add_i32 m0, s41, 0xc000
	ds_read_b128 v[160:163], v205
	ds_read_b128 v[164:167], v205 offset:1024
	ds_read_b128 v[168:171], v205 offset:2048
	ds_read_b128 v[188:191], v205 offset:3072
	ds_read_b128 v[192:195], v205 offset:4096
	ds_read_b128 v[196:199], v205 offset:5120
	ds_read_b128 v[208:211], v205 offset:6144
	global_load_lds_dwordx4 v180, s[34:35]
	s_add_i32 m0, s41, 0xe000
	ds_read_b128 v[212:215], v205 offset:7168
	global_load_lds_dwordx4 v182, s[34:35]
	s_waitcnt vmcnt(8) lgkmcnt(0)
	s_barrier
	s_setprio 1
	v_mfma_f32_16x16x32_bf16 v[140:143], v[56:59], v[160:163], v[140:143]
	v_mfma_f32_16x16x32_bf16 v[136:139], v[72:75], v[160:163], v[136:139]
	v_mfma_f32_16x16x32_bf16 v[124:127], v[56:59], v[168:171], v[124:127]
	v_mfma_f32_16x16x32_bf16 v[120:123], v[72:75], v[168:171], v[120:123]
	v_mfma_f32_16x16x32_bf16 v[108:111], v[56:59], v[192:195], v[108:111]
	v_mfma_f32_16x16x32_bf16 v[104:107], v[72:75], v[192:195], v[104:107]
	v_mfma_f32_16x16x32_bf16 v[92:95], v[56:59], v[208:211], v[92:95]
	v_mfma_f32_16x16x32_bf16 v[88:91], v[72:75], v[208:211], v[88:91]
	v_mfma_f32_16x16x32_bf16 v[140:143], v[64:67], v[164:167], v[140:143]
	v_mfma_f32_16x16x32_bf16 v[136:139], v[76:79], v[164:167], v[136:139]
	v_mfma_f32_16x16x32_bf16 v[124:127], v[64:67], v[188:191], v[124:127]
	v_mfma_f32_16x16x32_bf16 v[120:123], v[76:79], v[188:191], v[120:123]
	v_mfma_f32_16x16x32_bf16 v[108:111], v[64:67], v[196:199], v[108:111]
	v_mfma_f32_16x16x32_bf16 v[104:107], v[76:79], v[196:199], v[104:107]
	v_mfma_f32_16x16x32_bf16 v[92:95], v[64:67], v[212:215], v[92:95]
	v_mfma_f32_16x16x32_bf16 v[88:91], v[76:79], v[212:215], v[88:91]
	s_setprio 0
	s_setprio 1
	v_mfma_f32_16x16x32_bf16 v[132:135], v[144:147], v[160:163], v[132:135]
	v_mfma_f32_16x16x32_bf16 v[128:131], v[152:155], v[160:163], v[128:131]
	v_mfma_f32_16x16x32_bf16 v[116:119], v[144:147], v[168:171], v[116:119]
	v_mfma_f32_16x16x32_bf16 v[112:115], v[152:155], v[168:171], v[112:115]
	v_mfma_f32_16x16x32_bf16 v[100:103], v[144:147], v[192:195], v[100:103]
	v_mfma_f32_16x16x32_bf16 v[96:99], v[152:155], v[192:195], v[96:99]
	v_mfma_f32_16x16x32_bf16 v[84:87], v[144:147], v[208:211], v[84:87]
	v_mfma_f32_16x16x32_bf16 v[80:83], v[152:155], v[208:211], v[80:83]
	v_mfma_f32_16x16x32_bf16 v[132:135], v[148:151], v[164:167], v[132:135]
	v_mfma_f32_16x16x32_bf16 v[128:131], v[156:159], v[164:167], v[128:131]
	v_mfma_f32_16x16x32_bf16 v[116:119], v[148:151], v[188:191], v[116:119]
	v_mfma_f32_16x16x32_bf16 v[112:115], v[156:159], v[188:191], v[112:115]
	v_mfma_f32_16x16x32_bf16 v[100:103], v[148:151], v[196:199], v[100:103]
	v_mfma_f32_16x16x32_bf16 v[96:99], v[156:159], v[196:199], v[96:99]
	v_mfma_f32_16x16x32_bf16 v[84:87], v[148:151], v[212:215], v[84:87]
	v_mfma_f32_16x16x32_bf16 v[80:83], v[156:159], v[212:215], v[80:83]
	s_setprio 0
	s_barrier
	s_add_i32 s57, s49, s40
	s_add_u32 vcc_lo, s36, 0x80
	s_addc_u32 vcc_hi, s37, 0
	s_mov_b32 m0, s57
	ds_read_b128 v[160:163], v205 offset:16384
	ds_read_b128 v[164:167], v205 offset:17408
	ds_read_b128 v[168:171], v205 offset:18432
	ds_read_b128 v[188:191], v205 offset:19456
	global_load_lds_dwordx4 v174, s[36:37]
	s_add_i32 m0, s57, 0x2000
	s_add_u32 s58, s36, 0x80000
	s_addc_u32 s59, s37, 0
	s_add_i32 s57, s50, s40
	global_load_lds_dwordx4 v178, s[36:37]
	s_mov_b32 m0, s57
	ds_read_b128 v[212:215], v205 offset:23552
	global_load_lds_dwordx4 v174, s[58:59]
	s_add_i32 m0, s57, 0x2000
	ds_read_b128 v[208:211], v205 offset:22528
	global_load_lds_dwordx4 v178, s[58:59]
	s_add_u32 s98, s38, 0x80
	s_addc_u32 s99, s39, 0
	s_mov_b32 m0, s41
	ds_read_b128 v[196:199], v205 offset:21504
	global_load_lds_dwordx4 v172, s[38:39]
	s_mov_b32 m0, s42
	ds_read_b128 v[192:195], v205 offset:20480
	global_load_lds_dwordx4 v176, s[38:39]
	s_waitcnt vmcnt(8) lgkmcnt(0)
	s_barrier
	s_setprio 1
	v_mfma_f32_16x16x32_bf16 v[68:71], v[56:59], v[160:163], v[68:71]
	v_mfma_f32_16x16x32_bf16 v[60:63], v[72:75], v[160:163], v[60:63]
	v_mfma_f32_16x16x32_bf16 v[44:47], v[56:59], v[168:171], v[44:47]
	v_mfma_f32_16x16x32_bf16 v[40:43], v[72:75], v[168:171], v[40:43]
	v_mfma_f32_16x16x32_bf16 v[28:31], v[56:59], v[192:195], v[28:31]
	v_mfma_f32_16x16x32_bf16 v[24:27], v[72:75], v[192:195], v[24:27]
	v_mfma_f32_16x16x32_bf16 v[12:15], v[56:59], v[208:211], v[12:15]
	v_mfma_f32_16x16x32_bf16 v[8:11], v[72:75], v[208:211], v[8:11]
	v_mfma_f32_16x16x32_bf16 v[68:71], v[64:67], v[164:167], v[68:71]
	v_mfma_f32_16x16x32_bf16 v[60:63], v[76:79], v[164:167], v[60:63]
	v_mfma_f32_16x16x32_bf16 v[44:47], v[64:67], v[188:191], v[44:47]
	v_mfma_f32_16x16x32_bf16 v[40:43], v[76:79], v[188:191], v[40:43]
	v_mfma_f32_16x16x32_bf16 v[28:31], v[64:67], v[196:199], v[28:31]
	v_mfma_f32_16x16x32_bf16 v[24:27], v[76:79], v[196:199], v[24:27]
	v_mfma_f32_16x16x32_bf16 v[12:15], v[64:67], v[212:215], v[12:15]
	v_mfma_f32_16x16x32_bf16 v[8:11], v[76:79], v[212:215], v[8:11]
	s_setprio 0
	s_setprio 1
	v_mfma_f32_16x16x32_bf16 v[52:55], v[144:147], v[160:163], v[52:55]
	v_mfma_f32_16x16x32_bf16 v[48:51], v[152:155], v[160:163], v[48:51]
	v_mfma_f32_16x16x32_bf16 v[36:39], v[144:147], v[168:171], v[36:39]
	v_mfma_f32_16x16x32_bf16 v[32:35], v[152:155], v[168:171], v[32:35]
	v_mfma_f32_16x16x32_bf16 v[20:23], v[144:147], v[192:195], v[20:23]
	v_mfma_f32_16x16x32_bf16 v[16:19], v[152:155], v[192:195], v[16:19]
	v_mfma_f32_16x16x32_bf16 v[4:7], v[144:147], v[208:211], v[4:7]
	v_mfma_f32_16x16x32_bf16 v[0:3], v[152:155], v[208:211], v[0:3]
	v_mfma_f32_16x16x32_bf16 v[52:55], v[148:151], v[164:167], v[52:55]
	v_mfma_f32_16x16x32_bf16 v[48:51], v[156:159], v[164:167], v[48:51]
	v_mfma_f32_16x16x32_bf16 v[36:39], v[148:151], v[188:191], v[36:39]
	v_mfma_f32_16x16x32_bf16 v[32:35], v[156:159], v[188:191], v[32:35]
	v_mfma_f32_16x16x32_bf16 v[20:23], v[148:151], v[196:199], v[20:23]
	v_mfma_f32_16x16x32_bf16 v[16:19], v[156:159], v[196:199], v[16:19]
	v_mfma_f32_16x16x32_bf16 v[4:7], v[148:151], v[212:215], v[4:7]
	v_mfma_f32_16x16x32_bf16 v[0:3], v[156:159], v[212:215], v[0:3]
	s_setprio 0
	s_barrier
; #define PG8_STAGE(bufoff, gbase, voff) do { _Pragma("unroll") for (int _i = 0; _i < 2; ++_i) \
;         __builtin_amdgcn_global_load_lds((const unsigned*)((const char*)(gbase) + (voff)[_i]), (PG8_LAS unsigned*)(lds + (bufoff) + ldsw + _i * 8192), 16, 0, 0); } while (0)
; #define PG8_LDA(dst, b, h) do { _Pragma("unroll") for (int m = 0; m < 4; ++m) _Pragma("unroll") for (int k = 0; k < 2; ++k) dst[m][k] = *(const PG8_LAS bf16x8*)(lds + PG8_SA(b, h) + aoff + m * 2048 + k * 1024); } while (0)
; #define PG8_LDB(dst, b, h) do { _Pragma("unroll") for (int n = 0; n < 2; ++n) _Pragma("unroll") for (int k = 0; k < 2; ++k) dst[n][k] = *(const PG8_LAS bf16x8*)(lds + PG8_SB(b, h) + boff + n * 2048 + k * 1024); } while (0)
; #define PG8_MMA(ai, bj, At, Bt) do { __builtin_amdgcn_s_setprio(1); _Pragma("unroll") for (int m = 0; m < 4; ++m) _Pragma("unroll") for (int n = 0; n < 2; ++n) _Pragma("unroll") for (int k = 0; k < 2; ++k) \
;         acc[ai][bj][m][n] = __builtin_amdgcn_mfma_f32_16x16x32_bf16(Bt[n][k], At[m][k], acc[ai][bj][m][n], 0, 0, 0); __builtin_amdgcn_s_setprio(0); } while (0)
; #define PG8_WAIT_V(n) asm volatile("s_waitcnt vmcnt(" #n ")" ::: "memory")
; #define PG8_WAIT_L(n) asm volatile("s_waitcnt lgkmcnt(" #n ")" ::: "memory")
; #define PG8_BAR __builtin_amdgcn_s_barrier()
; #define PG8_SCHED __builtin_amdgcn_sched_barrier(0)
; template <class Epi, class Sched, bool ALIGN_EPI = false, bool SP2 = false>
; __device__ __forceinline__ void gemm_phase(PG8_LAS unsigned char* lds, const Gemm g, const Sched& S, const Epi& E) {
;     ...
;             PG8_LDB(B0, 1, 0); PG8_LDB(B1, 1, 1); PG8_SCHED; PG8_LDA(At, 1, 0); PG8_STAGE(PG8_SA(0, 1), a2 + hstep, voffA);
;             PG8_WAIT_V(8); PG8_WAIT_L(0); PG8_BAR; PG8_MMA(0, 0, At, B0); PG8_MMA(0, 1, At, B1); PG8_BAR; PG8_SCHED;
;             PG8_LDA(At, 1, 1); PG8_STAGE(PG8_SB(1, 0), b3, voffB); PG8_STAGE(PG8_SB(1, 1), b3 + hstep, voffB); PG8_STAGE(PG8_SA(1, 0), a3, voffA);
;             PG8_WAIT_V(8); PG8_WAIT_L(0); PG8_BAR; PG8_MMA(1, 0, At, B0); PG8_MMA(1, 1, At, B1); PG8_BAR; PG8_SCHED;
	s_add_i32 s57, 0, 0x18000
	s_add_i32 s58, 0, 0x1c000
	v_add_u32_e32 v76, s57, v201
	v_add_u32_e32 v156, s58, v201
	ds_read_b128 v[56:59], v76
	ds_read_b128 v[64:67], v76 offset:1024
	ds_read_b128 v[72:75], v76 offset:2048
	ds_read_b128 v[76:79], v76 offset:3072
	ds_read_b128 v[144:147], v156
	ds_read_b128 v[148:151], v156 offset:1024
	ds_read_b128 v[152:155], v156 offset:2048
	ds_read_b128 v[156:159], v156 offset:3072
	s_add_u32 s38, s38, 0x80000
	s_addc_u32 s39, s39, 0
	s_mov_b32 m0, s43
	ds_read_b128 v[160:163], v205 offset:32768
	ds_read_b128 v[164:167], v205 offset:33792
	ds_read_b128 v[168:171], v205 offset:34816
	ds_read_b128 v[188:191], v205 offset:35840
	ds_read_b128 v[192:195], v205 offset:36864
	ds_read_b128 v[196:199], v205 offset:37888
	ds_read_b128 v[208:211], v205 offset:38912
	global_load_lds_dwordx4 v172, s[38:39]
	s_mov_b32 m0, s44
	ds_read_b128 v[212:215], v205 offset:39936
	global_load_lds_dwordx4 v176, s[38:39]
	s_waitcnt vmcnt(8) lgkmcnt(0)
	s_barrier
	s_setprio 1
	v_mfma_f32_16x16x32_bf16 v[140:143], v[56:59], v[160:163], v[140:143]
	v_mfma_f32_16x16x32_bf16 v[136:139], v[72:75], v[160:163], v[136:139]
	v_mfma_f32_16x16x32_bf16 v[124:127], v[56:59], v[168:171], v[124:127]
	v_mfma_f32_16x16x32_bf16 v[120:123], v[72:75], v[168:171], v[120:123]
	v_mfma_f32_16x16x32_bf16 v[108:111], v[56:59], v[192:195], v[108:111]
	v_mfma_f32_16x16x32_bf16 v[104:107], v[72:75], v[192:195], v[104:107]
	v_mfma_f32_16x16x32_bf16 v[92:95], v[56:59], v[208:211], v[92:95]
	v_mfma_f32_16x16x32_bf16 v[88:91], v[72:75], v[208:211], v[88:91]
	v_mfma_f32_16x16x32_bf16 v[140:143], v[64:67], v[164:167], v[140:143]
	v_mfma_f32_16x16x32_bf16 v[136:139], v[76:79], v[164:167], v[136:139]
	v_mfma_f32_16x16x32_bf16 v[124:127], v[64:67], v[188:191], v[124:127]
	v_mfma_f32_16x16x32_bf16 v[120:123], v[76:79], v[188:191], v[120:123]
	v_mfma_f32_16x16x32_bf16 v[108:111], v[64:67], v[196:199], v[108:111]
	v_mfma_f32_16x16x32_bf16 v[104:107], v[76:79], v[196:199], v[104:107]
	v_mfma_f32_16x16x32_bf16 v[92:95], v[64:67], v[212:215], v[92:95]
	v_mfma_f32_16x16x32_bf16 v[88:91], v[76:79], v[212:215], v[88:91]
	s_setprio 0
	s_setprio 1
	v_mfma_f32_16x16x32_bf16 v[132:135], v[144:147], v[160:163], v[132:135]
	v_mfma_f32_16x16x32_bf16 v[128:131], v[152:155], v[160:163], v[128:131]
	v_mfma_f32_16x16x32_bf16 v[116:119], v[144:147], v[168:171], v[116:119]
	v_mfma_f32_16x16x32_bf16 v[112:115], v[152:155], v[168:171], v[112:115]
	v_mfma_f32_16x16x32_bf16 v[100:103], v[144:147], v[192:195], v[100:103]
	v_mfma_f32_16x16x32_bf16 v[96:99], v[152:155], v[192:195], v[96:99]
	v_mfma_f32_16x16x32_bf16 v[84:87], v[144:147], v[208:211], v[84:87]
	v_mfma_f32_16x16x32_bf16 v[80:83], v[152:155], v[208:211], v[80:83]
	v_mfma_f32_16x16x32_bf16 v[132:135], v[148:151], v[164:167], v[132:135]
	v_mfma_f32_16x16x32_bf16 v[128:131], v[156:159], v[164:167], v[128:131]
	v_mfma_f32_16x16x32_bf16 v[116:119], v[148:151], v[188:191], v[116:119]
	v_mfma_f32_16x16x32_bf16 v[112:115], v[156:159], v[188:191], v[112:115]
	v_mfma_f32_16x16x32_bf16 v[100:103], v[148:151], v[196:199], v[100:103]
	v_mfma_f32_16x16x32_bf16 v[96:99], v[156:159], v[196:199], v[96:99]
	v_mfma_f32_16x16x32_bf16 v[84:87], v[148:151], v[212:215], v[84:87]
	v_mfma_f32_16x16x32_bf16 v[80:83], v[156:159], v[212:215], v[80:83]
	s_setprio 0
	s_barrier
	s_add_i32 s38, s57, s40
	s_mov_b32 m0, s38
	ds_read_b128 v[160:163], v205 offset:49152
	ds_read_b128 v[164:167], v205 offset:50176
	ds_read_b128 v[168:171], v205 offset:51200
	ds_read_b128 v[188:191], v205 offset:52224
	global_load_lds_dwordx4 v174, vcc
	s_add_i32 m0, s38, 0x2000
	s_add_u32 s36, s36, 0x80080
	s_addc_u32 s37, s37, 0
	s_add_i32 s38, s58, s40
	global_load_lds_dwordx4 v178, vcc
	s_mov_b32 m0, s38
	ds_read_b128 v[212:215], v205 offset:56320
	global_load_lds_dwordx4 v174, s[36:37]
	s_add_i32 m0, s38, 0x2000
	ds_read_b128 v[208:211], v205 offset:55296
	global_load_lds_dwordx4 v178, s[36:37]
	s_mov_b32 m0, s46
	ds_read_b128 v[196:199], v205 offset:54272
	global_load_lds_dwordx4 v172, s[98:99]
	s_mov_b32 m0, s47
	ds_read_b128 v[192:195], v205 offset:53248
	global_load_lds_dwordx4 v176, s[98:99]
	s_waitcnt vmcnt(8) lgkmcnt(0)
	s_barrier
	s_setprio 1
	v_mfma_f32_16x16x32_bf16 v[68:71], v[56:59], v[160:163], v[68:71]
	v_mfma_f32_16x16x32_bf16 v[60:63], v[72:75], v[160:163], v[60:63]
	v_mfma_f32_16x16x32_bf16 v[44:47], v[56:59], v[168:171], v[44:47]
	v_mfma_f32_16x16x32_bf16 v[40:43], v[72:75], v[168:171], v[40:43]
	v_mfma_f32_16x16x32_bf16 v[28:31], v[56:59], v[192:195], v[28:31]
	v_mfma_f32_16x16x32_bf16 v[24:27], v[72:75], v[192:195], v[24:27]
	v_mfma_f32_16x16x32_bf16 v[12:15], v[56:59], v[208:211], v[12:15]
	v_mfma_f32_16x16x32_bf16 v[8:11], v[72:75], v[208:211], v[8:11]
	v_mfma_f32_16x16x32_bf16 v[68:71], v[64:67], v[164:167], v[68:71]
	v_mfma_f32_16x16x32_bf16 v[60:63], v[76:79], v[164:167], v[60:63]
	v_mfma_f32_16x16x32_bf16 v[44:47], v[64:67], v[188:191], v[44:47]
	v_mfma_f32_16x16x32_bf16 v[40:43], v[76:79], v[188:191], v[40:43]
	v_mfma_f32_16x16x32_bf16 v[28:31], v[64:67], v[196:199], v[28:31]
	v_mfma_f32_16x16x32_bf16 v[24:27], v[76:79], v[196:199], v[24:27]
	v_mfma_f32_16x16x32_bf16 v[12:15], v[64:67], v[212:215], v[12:15]
	v_mfma_f32_16x16x32_bf16 v[8:11], v[76:79], v[212:215], v[8:11]
	s_setprio 0
	s_setprio 1
	v_mfma_f32_16x16x32_bf16 v[52:55], v[144:147], v[160:163], v[52:55]
	v_mfma_f32_16x16x32_bf16 v[48:51], v[152:155], v[160:163], v[48:51]
	v_mfma_f32_16x16x32_bf16 v[36:39], v[144:147], v[168:171], v[36:39]
	v_mfma_f32_16x16x32_bf16 v[32:35], v[152:155], v[168:171], v[32:35]
	v_mfma_f32_16x16x32_bf16 v[20:23], v[144:147], v[192:195], v[20:23]
	v_mfma_f32_16x16x32_bf16 v[16:19], v[152:155], v[192:195], v[16:19]
	v_mfma_f32_16x16x32_bf16 v[4:7], v[144:147], v[208:211], v[4:7]
	v_mfma_f32_16x16x32_bf16 v[0:3], v[152:155], v[208:211], v[0:3]
	v_mfma_f32_16x16x32_bf16 v[52:55], v[148:151], v[164:167], v[52:55]
	v_mfma_f32_16x16x32_bf16 v[48:51], v[156:159], v[164:167], v[48:51]
	v_mfma_f32_16x16x32_bf16 v[36:39], v[148:151], v[188:191], v[36:39]
	v_mfma_f32_16x16x32_bf16 v[32:35], v[156:159], v[188:191], v[32:35]
	v_mfma_f32_16x16x32_bf16 v[20:23], v[148:151], v[196:199], v[20:23]
	v_mfma_f32_16x16x32_bf16 v[16:19], v[156:159], v[196:199], v[16:19]
	v_mfma_f32_16x16x32_bf16 v[4:7], v[148:151], v[212:215], v[4:7]
	v_mfma_f32_16x16x32_bf16 v[0:3], v[156:159], v[212:215], v[0:3]
	s_setprio 0
	s_barrier
	s_add_i32 s56, s56, 2
	s_add_u32 s34, s34, 0x100
	s_addc_u32 s35, s35, 0
	s_add_u32 s54, s54, 0x100
	s_addc_u32 s55, s55, 0
	s_cmp_gt_u32 s56, 29
	s_cbranch_scc0 .LBB0_1295
	s_and_b64 vcc, exec, s[16:17]
	s_cbranch_vccz .LBB0_1298
	s_barrier
